# ss loads of the swiglu and w_in epilogues issued right after the K-loop exit, before the tile-claim section (latency overlapped with the claim round trip)
# baseline (speedup 1.0000x reference)
; __device__ __forceinline__ void h_main(f32x16 (&acc0)[2][2], f32x16 (&acc1)[2][2], const WideCtx& c, int nk, char* lds) {
;   const int h = c.h;
;   for (int kt = 0; kt < nk; ++kt) {
;     asm volatile("s_waitcnt vmcnt(0)" ::: "memory");
;     __builtin_amdgcn_s_barrier();
;     if (kt + 1 < nk) h_stage(c, kt + 1);
;     const char* st = lds + (kt & 1) * 24576;
; #pragma unroll
;     for (int ks = 0; ks < 2; ++ks) {
;       bf16x8 wf[2], a0[2], a1[2];
; #pragma unroll
;       for (int b = 0; b < 2; ++b) {
;         wf[b] = *(const bf16x8*)(st + c.wro[b] + (((ks * 2 + h) ^ c.wsw[b]) << 4));
;         a0[b] = *(const bf16x8*)(st + c.aro[0][b] + (((ks * 2 + h) ^ c.asw[0][b]) << 4));
;         a1[b] = *(const bf16x8*)(st + c.aro[1][b] + (((ks * 2 + h) ^ c.asw[1][b]) << 4));
;       }
; #pragma unroll
;       for (int nb = 0; nb < 2; ++nb)
; #pragma unroll
;         for (int tb = 0; tb < 2; ++tb) {
;           acc0[nb][tb] = __builtin_amdgcn_mfma_f32_32x32x16_bf16(wf[nb], a0[tb], acc0[nb][tb], 0, 0, 0);
;           acc1[nb][tb] = __builtin_amdgcn_mfma_f32_32x32x16_bf16(wf[nb], a1[tb], acc1[nb][tb], 0, 0, 0);
;         }
;     }
;   }
; }
.LBB0_86:
	s_waitcnt vmcnt(6)
	s_barrier
	v_add_u32_e32 v171, s6, v248
	v_add_u32_e32 v196, s6, v249
	ds_read_b128 v[172:175], v171
	ds_read_b128 v[176:179], v196 offset:8192
	ds_read_b128 v[188:191], v196 offset:9216
	ds_read_b128 v[180:183], v196 offset:10240
	ds_read_b128 v[192:195], v196 offset:11264
	ds_read_b128 v[230:233], v196 offset:16384
	ds_read_b128 v[234:237], v196 offset:17408
	ds_read_b128 v[238:241], v196 offset:18432
	ds_read_b128 v[242:245], v196 offset:19456
	ds_read_b128 v[184:187], v171 offset:1024
	ds_read_b128 v[222:225], v171 offset:2048
	ds_read_b128 v[226:229], v171 offset:3072
	s_add_i32 s7, s6, 0xffffa000
	s_cmp_eq_u32 s6, 0
	s_cselect_b32 s7, 0xc000, s7
	s_add_i32 m0, s7, s48
	s_add_i32 s7, s6, 0x6000
	global_load_lds_dwordx4 v154, s[0:1]
	s_add_i32 m0, m0, 0x1000
	s_cmp_eq_u32 s6, 0xc000
	global_load_lds_dwordx4 v152, s[0:1]
	s_cselect_b32 s6, 0, s7
	s_add_i32 m0, m0, 0x1000
	s_waitcnt lgkmcnt(10)
	v_mfma_f32_16x16x32_bf16 v[112:115], v[172:175], v[176:179], v[112:115]
	global_load_lds_dwordx4 v150, s[0:1]
	s_add_i32 m0, m0, 0x1000
	s_waitcnt lgkmcnt(9)
	v_mfma_f32_16x16x32_bf16 v[116:119], v[172:175], v[188:191], v[116:119]
	global_load_lds_dwordx4 v148, s[0:1]
	s_add_i32 m0, m0, 0x1000
	s_waitcnt lgkmcnt(8)
	v_mfma_f32_16x16x32_bf16 v[80:83], v[172:175], v[180:183], v[80:83]
	global_load_lds_dwordx4 v146, s[0:1]
	s_add_i32 m0, m0, 0x1000
	s_waitcnt lgkmcnt(7)
	v_mfma_f32_16x16x32_bf16 v[84:87], v[172:175], v[192:195], v[84:87]
	global_load_lds_dwordx4 v144, s[0:1]
	s_add_u32 s0, s0, 64
	s_addc_u32 s1, s1, 0
	s_waitcnt lgkmcnt(6)
	v_mfma_f32_16x16x32_bf16 v[48:51], v[172:175], v[230:233], v[48:51]
	s_waitcnt lgkmcnt(5)
	v_mfma_f32_16x16x32_bf16 v[52:55], v[172:175], v[234:237], v[52:55]
	s_waitcnt lgkmcnt(4)
	v_mfma_f32_16x16x32_bf16 v[16:19], v[172:175], v[238:241], v[16:19]
	s_waitcnt lgkmcnt(3)
	v_mfma_f32_16x16x32_bf16 v[20:23], v[172:175], v[242:245], v[20:23]
	s_waitcnt lgkmcnt(2)
	v_mfma_f32_16x16x32_bf16 v[120:123], v[184:187], v[176:179], v[120:123]
	v_mfma_f32_16x16x32_bf16 v[124:127], v[184:187], v[188:191], v[124:127]
	v_mfma_f32_16x16x32_bf16 v[88:91], v[184:187], v[180:183], v[88:91]
	v_mfma_f32_16x16x32_bf16 v[92:95], v[184:187], v[192:195], v[92:95]
	v_mfma_f32_16x16x32_bf16 v[56:59], v[184:187], v[230:233], v[56:59]
	v_mfma_f32_16x16x32_bf16 v[60:63], v[184:187], v[234:237], v[60:63]
	v_mfma_f32_16x16x32_bf16 v[24:27], v[184:187], v[238:241], v[24:27]
	v_mfma_f32_16x16x32_bf16 v[28:31], v[184:187], v[242:245], v[28:31]
	s_waitcnt lgkmcnt(1)
	v_mfma_f32_16x16x32_bf16 v[96:99], v[222:225], v[176:179], v[96:99]
	v_mfma_f32_16x16x32_bf16 v[100:103], v[222:225], v[188:191], v[100:103]
	v_mfma_f32_16x16x32_bf16 v[64:67], v[222:225], v[180:183], v[64:67]
	v_mfma_f32_16x16x32_bf16 v[68:71], v[222:225], v[192:195], v[68:71]
	v_mfma_f32_16x16x32_bf16 v[32:35], v[222:225], v[230:233], v[32:35]
	v_mfma_f32_16x16x32_bf16 v[36:39], v[222:225], v[234:237], v[36:39]
	v_mfma_f32_16x16x32_bf16 v[0:3], v[222:225], v[238:241], v[0:3]
	v_mfma_f32_16x16x32_bf16 v[4:7], v[222:225], v[242:245], v[4:7]
	s_waitcnt lgkmcnt(0)
	v_mfma_f32_16x16x32_bf16 v[104:107], v[226:229], v[176:179], v[104:107]
	v_mfma_f32_16x16x32_bf16 v[108:111], v[226:229], v[188:191], v[108:111]
	v_mfma_f32_16x16x32_bf16 v[72:75], v[226:229], v[180:183], v[72:75]
	v_mfma_f32_16x16x32_bf16 v[76:79], v[226:229], v[192:195], v[76:79]
	v_mfma_f32_16x16x32_bf16 v[40:43], v[226:229], v[230:233], v[40:43]
	v_mfma_f32_16x16x32_bf16 v[44:47], v[226:229], v[234:237], v[44:47]
	v_mfma_f32_16x16x32_bf16 v[8:11], v[226:229], v[238:241], v[8:11]
	v_mfma_f32_16x16x32_bf16 v[12:15], v[226:229], v[242:245], v[12:15]
	s_add_i32 s9, s9, 1
	s_cmp_eq_u32 s9, 32
	s_cbranch_scc0 .LBB0_86
	s_waitcnt vmcnt(6)
	s_barrier
	v_add_u32_e32 v171, s6, v248
	v_add_u32_e32 v196, s6, v249
	ds_read_b128 v[172:175], v171
	ds_read_b128 v[176:179], v196 offset:8192
	ds_read_b128 v[188:191], v196 offset:9216
	ds_read_b128 v[180:183], v196 offset:10240
	ds_read_b128 v[192:195], v196 offset:11264
	ds_read_b128 v[230:233], v196 offset:16384
	ds_read_b128 v[234:237], v196 offset:17408
	ds_read_b128 v[238:241], v196 offset:18432
	ds_read_b128 v[242:245], v196 offset:19456
	ds_read_b128 v[184:187], v171 offset:1024
	ds_read_b128 v[222:225], v171 offset:2048
	ds_read_b128 v[226:229], v171 offset:3072
	s_add_i32 s7, s6, 0x6000
	s_cmp_eq_u32 s6, 0xc000
	s_cselect_b32 s6, 0, s7
	s_waitcnt lgkmcnt(10)
	v_mfma_f32_16x16x32_bf16 v[112:115], v[172:175], v[176:179], v[112:115]
	s_waitcnt lgkmcnt(9)
	v_mfma_f32_16x16x32_bf16 v[116:119], v[172:175], v[188:191], v[116:119]
	s_waitcnt lgkmcnt(8)
	v_mfma_f32_16x16x32_bf16 v[80:83], v[172:175], v[180:183], v[80:83]
	s_waitcnt lgkmcnt(7)
	v_mfma_f32_16x16x32_bf16 v[84:87], v[172:175], v[192:195], v[84:87]
	s_waitcnt lgkmcnt(6)
	v_mfma_f32_16x16x32_bf16 v[48:51], v[172:175], v[230:233], v[48:51]
	s_waitcnt lgkmcnt(5)
	v_mfma_f32_16x16x32_bf16 v[52:55], v[172:175], v[234:237], v[52:55]
	s_waitcnt lgkmcnt(4)
	v_mfma_f32_16x16x32_bf16 v[16:19], v[172:175], v[238:241], v[16:19]
	s_waitcnt lgkmcnt(3)
	v_mfma_f32_16x16x32_bf16 v[20:23], v[172:175], v[242:245], v[20:23]
	s_waitcnt lgkmcnt(2)
	v_mfma_f32_16x16x32_bf16 v[120:123], v[184:187], v[176:179], v[120:123]
	v_mfma_f32_16x16x32_bf16 v[124:127], v[184:187], v[188:191], v[124:127]
	v_mfma_f32_16x16x32_bf16 v[88:91], v[184:187], v[180:183], v[88:91]
	v_mfma_f32_16x16x32_bf16 v[92:95], v[184:187], v[192:195], v[92:95]
	v_mfma_f32_16x16x32_bf16 v[56:59], v[184:187], v[230:233], v[56:59]
	v_mfma_f32_16x16x32_bf16 v[60:63], v[184:187], v[234:237], v[60:63]
	v_mfma_f32_16x16x32_bf16 v[24:27], v[184:187], v[238:241], v[24:27]
	v_mfma_f32_16x16x32_bf16 v[28:31], v[184:187], v[242:245], v[28:31]
	s_waitcnt lgkmcnt(1)
	v_mfma_f32_16x16x32_bf16 v[96:99], v[222:225], v[176:179], v[96:99]
	v_mfma_f32_16x16x32_bf16 v[100:103], v[222:225], v[188:191], v[100:103]
	v_mfma_f32_16x16x32_bf16 v[64:67], v[222:225], v[180:183], v[64:67]
	v_mfma_f32_16x16x32_bf16 v[68:71], v[222:225], v[192:195], v[68:71]
	v_mfma_f32_16x16x32_bf16 v[32:35], v[222:225], v[230:233], v[32:35]
	v_mfma_f32_16x16x32_bf16 v[36:39], v[222:225], v[234:237], v[36:39]
	v_mfma_f32_16x16x32_bf16 v[0:3], v[222:225], v[238:241], v[0:3]
	v_mfma_f32_16x16x32_bf16 v[4:7], v[222:225], v[242:245], v[4:7]
	s_waitcnt lgkmcnt(0)
	v_mfma_f32_16x16x32_bf16 v[104:107], v[226:229], v[176:179], v[104:107]
	v_mfma_f32_16x16x32_bf16 v[108:111], v[226:229], v[188:191], v[108:111]
	v_mfma_f32_16x16x32_bf16 v[72:75], v[226:229], v[180:183], v[72:75]
	v_mfma_f32_16x16x32_bf16 v[76:79], v[226:229], v[192:195], v[76:79]
	v_mfma_f32_16x16x32_bf16 v[40:43], v[226:229], v[230:233], v[40:43]
	v_mfma_f32_16x16x32_bf16 v[44:47], v[226:229], v[234:237], v[44:47]
	v_mfma_f32_16x16x32_bf16 v[8:11], v[226:229], v[238:241], v[8:11]
	v_mfma_f32_16x16x32_bf16 v[12:15], v[226:229], v[242:245], v[12:15]
	s_waitcnt vmcnt(0)
	s_barrier
; __device__ __forceinline__ void h_main(f32x16 (&acc0)[2][2], f32x16 (&acc1)[2][2], const WideCtx& c, int nk, char* lds) {
;   const int h = c.h;
;   for (int kt = 0; kt < nk; ++kt) {
;     asm volatile("s_waitcnt vmcnt(0)" ::: "memory");
;     __builtin_amdgcn_s_barrier();
;     if (kt + 1 < nk) h_stage(c, kt + 1);
;     const char* st = lds + (kt & 1) * 24576;
; #pragma unroll
;     for (int ks = 0; ks < 2; ++ks) {
;       bf16x8 wf[2], a0[2], a1[2];
; #pragma unroll
;       for (int b = 0; b < 2; ++b) {
;         wf[b] = *(const bf16x8*)(st + c.wro[b] + (((ks * 2 + h) ^ c.wsw[b]) << 4));
;         a0[b] = *(const bf16x8*)(st + c.aro[0][b] + (((ks * 2 + h) ^ c.asw[0][b]) << 4));
;         a1[b] = *(const bf16x8*)(st + c.aro[1][b] + (((ks * 2 + h) ^ c.asw[1][b]) << 4));
;       }
; #pragma unroll
;       for (int nb = 0; nb < 2; ++nb)
; #pragma unroll
;         for (int tb = 0; tb < 2; ++tb) {
;           acc0[nb][tb] = __builtin_amdgcn_mfma_f32_32x32x16_bf16(wf[nb], a0[tb], acc0[nb][tb], 0, 0, 0);
;           acc1[nb][tb] = __builtin_amdgcn_mfma_f32_32x32x16_bf16(wf[nb], a1[tb], acc1[nb][tb], 0, 0, 0);
;         }
;     }
;   }
; }
	v_add_u32_e32 v171, s6, v248
	v_add_u32_e32 v196, s6, v249
	ds_read_b128 v[172:175], v171
	ds_read_b128 v[176:179], v196 offset:8192
	ds_read_b128 v[188:191], v196 offset:9216
	ds_read_b128 v[180:183], v196 offset:10240
	ds_read_b128 v[192:195], v196 offset:11264
	ds_read_b128 v[230:233], v196 offset:16384
	ds_read_b128 v[234:237], v196 offset:17408
	ds_read_b128 v[238:241], v196 offset:18432
	ds_read_b128 v[242:245], v196 offset:19456
	ds_read_b128 v[184:187], v171 offset:1024
	ds_read_b128 v[222:225], v171 offset:2048
	ds_read_b128 v[226:229], v171 offset:3072
	s_add_i32 s7, s6, 0x6000
	s_cmp_eq_u32 s6, 0xc000
	s_cselect_b32 s6, 0, s7
	s_waitcnt lgkmcnt(10)
	v_mfma_f32_16x16x32_bf16 v[112:115], v[172:175], v[176:179], v[112:115]
	s_waitcnt lgkmcnt(9)
	v_mfma_f32_16x16x32_bf16 v[116:119], v[172:175], v[188:191], v[116:119]
	s_waitcnt lgkmcnt(8)
	v_mfma_f32_16x16x32_bf16 v[80:83], v[172:175], v[180:183], v[80:83]
	s_waitcnt lgkmcnt(7)
	v_mfma_f32_16x16x32_bf16 v[84:87], v[172:175], v[192:195], v[84:87]
	s_waitcnt lgkmcnt(6)
	v_mfma_f32_16x16x32_bf16 v[48:51], v[172:175], v[230:233], v[48:51]
	s_waitcnt lgkmcnt(5)
	v_mfma_f32_16x16x32_bf16 v[52:55], v[172:175], v[234:237], v[52:55]
	s_waitcnt lgkmcnt(4)
	v_mfma_f32_16x16x32_bf16 v[16:19], v[172:175], v[238:241], v[16:19]
	s_waitcnt lgkmcnt(3)
	v_mfma_f32_16x16x32_bf16 v[20:23], v[172:175], v[242:245], v[20:23]
	s_waitcnt lgkmcnt(2)
	v_mfma_f32_16x16x32_bf16 v[120:123], v[184:187], v[176:179], v[120:123]
	v_mfma_f32_16x16x32_bf16 v[124:127], v[184:187], v[188:191], v[124:127]
	v_mfma_f32_16x16x32_bf16 v[88:91], v[184:187], v[180:183], v[88:91]
	v_mfma_f32_16x16x32_bf16 v[92:95], v[184:187], v[192:195], v[92:95]
	v_mfma_f32_16x16x32_bf16 v[56:59], v[184:187], v[230:233], v[56:59]
	v_mfma_f32_16x16x32_bf16 v[60:63], v[184:187], v[234:237], v[60:63]
	v_mfma_f32_16x16x32_bf16 v[24:27], v[184:187], v[238:241], v[24:27]
	v_mfma_f32_16x16x32_bf16 v[28:31], v[184:187], v[242:245], v[28:31]
	s_waitcnt lgkmcnt(1)
	v_mfma_f32_16x16x32_bf16 v[96:99], v[222:225], v[176:179], v[96:99]
	v_mfma_f32_16x16x32_bf16 v[100:103], v[222:225], v[188:191], v[100:103]
	v_mfma_f32_16x16x32_bf16 v[64:67], v[222:225], v[180:183], v[64:67]
	v_mfma_f32_16x16x32_bf16 v[68:71], v[222:225], v[192:195], v[68:71]
	v_mfma_f32_16x16x32_bf16 v[32:35], v[222:225], v[230:233], v[32:35]
	v_mfma_f32_16x16x32_bf16 v[36:39], v[222:225], v[234:237], v[36:39]
	v_mfma_f32_16x16x32_bf16 v[0:3], v[222:225], v[238:241], v[0:3]
	v_mfma_f32_16x16x32_bf16 v[4:7], v[222:225], v[242:245], v[4:7]
	s_waitcnt lgkmcnt(0)
; __device__ __forceinline__ void h_main(f32x16 (&acc0)[2][2], f32x16 (&acc1)[2][2], const WideCtx& c, int nk, char* lds) {
;     ...
;           acc0[nb][tb] = __builtin_amdgcn_mfma_f32_32x32x16_bf16(wf[nb], a0[tb], acc0[nb][tb], 0, 0, 0);
;           acc1[nb][tb] = __builtin_amdgcn_mfma_f32_32x32x16_bf16(wf[nb], a1[tb], acc1[nb][tb], 0, 0, 0);
; template <class F>
; __device__ __forceinline__ void gemm_phase_w(const u16* A, int lda, int M, const u16* W, int K, int N, char* lds, int* ctr, F&& epi) {
;     ...
;     const int ctm = tm, ctn = tn;
;     par ^= 1;
;     if (c.tid == 0) bw[2 + par] = atomicAdd(myctr, 1);
	v_mfma_f32_16x16x32_bf16 v[104:107], v[226:229], v[176:179], v[104:107]
	v_mfma_f32_16x16x32_bf16 v[108:111], v[226:229], v[188:191], v[108:111]
	v_mfma_f32_16x16x32_bf16 v[72:75], v[226:229], v[180:183], v[72:75]
	v_mfma_f32_16x16x32_bf16 v[76:79], v[226:229], v[192:195], v[76:79]
	v_mfma_f32_16x16x32_bf16 v[40:43], v[226:229], v[230:233], v[40:43]
	v_mfma_f32_16x16x32_bf16 v[44:47], v[226:229], v[234:237], v[44:47]
	v_mfma_f32_16x16x32_bf16 v[8:11], v[226:229], v[238:241], v[8:11]
	v_mfma_f32_16x16x32_bf16 v[12:15], v[226:229], v[242:245], v[12:15]
	s_xor_b32 s49, s49, 1
	s_nop 7
	s_nop 7
	v_permlane16_swap_b32_e32 v112, v116
	v_permlane16_swap_b32_e32 v113, v117
	v_permlane16_swap_b32_e32 v114, v118
	v_permlane16_swap_b32_e32 v115, v119
	v_permlane16_swap_b32_e32 v120, v124
	v_permlane16_swap_b32_e32 v121, v125
	v_permlane16_swap_b32_e32 v122, v126
	v_permlane16_swap_b32_e32 v123, v127
	v_permlane16_swap_b32_e32 v80, v84
	v_permlane16_swap_b32_e32 v81, v85
	v_permlane16_swap_b32_e32 v82, v86
	v_permlane16_swap_b32_e32 v83, v87
	v_permlane16_swap_b32_e32 v88, v92
	v_permlane16_swap_b32_e32 v89, v93
	v_permlane16_swap_b32_e32 v90, v94
	v_permlane16_swap_b32_e32 v91, v95
	v_permlane16_swap_b32_e32 v48, v52
	v_permlane16_swap_b32_e32 v49, v53
	v_permlane16_swap_b32_e32 v50, v54
	v_permlane16_swap_b32_e32 v51, v55
	v_permlane16_swap_b32_e32 v56, v60
	v_permlane16_swap_b32_e32 v57, v61
	v_permlane16_swap_b32_e32 v58, v62
	v_permlane16_swap_b32_e32 v59, v63
	v_permlane16_swap_b32_e32 v16, v20
	v_permlane16_swap_b32_e32 v17, v21
	v_permlane16_swap_b32_e32 v18, v22
	v_permlane16_swap_b32_e32 v19, v23
	v_permlane16_swap_b32_e32 v24, v28
	v_permlane16_swap_b32_e32 v25, v29
	v_permlane16_swap_b32_e32 v26, v30
	v_permlane16_swap_b32_e32 v27, v31
	v_permlane16_swap_b32_e32 v96, v100
	v_permlane16_swap_b32_e32 v97, v101
	v_permlane16_swap_b32_e32 v98, v102
	v_permlane16_swap_b32_e32 v99, v103
	v_permlane16_swap_b32_e32 v104, v108
	v_permlane16_swap_b32_e32 v105, v109
	v_permlane16_swap_b32_e32 v106, v110
	v_permlane16_swap_b32_e32 v107, v111
	v_permlane16_swap_b32_e32 v64, v68
	v_permlane16_swap_b32_e32 v65, v69
	v_permlane16_swap_b32_e32 v66, v70
	v_permlane16_swap_b32_e32 v67, v71
	v_permlane16_swap_b32_e32 v72, v76
	v_permlane16_swap_b32_e32 v73, v77
	v_permlane16_swap_b32_e32 v74, v78
	v_permlane16_swap_b32_e32 v75, v79
	v_permlane16_swap_b32_e32 v32, v36
	v_permlane16_swap_b32_e32 v33, v37
	v_permlane16_swap_b32_e32 v34, v38
	v_permlane16_swap_b32_e32 v35, v39
	v_permlane16_swap_b32_e32 v40, v44
	v_permlane16_swap_b32_e32 v41, v45
	v_permlane16_swap_b32_e32 v42, v46
	v_permlane16_swap_b32_e32 v43, v47
	v_permlane16_swap_b32_e32 v0, v4
	v_permlane16_swap_b32_e32 v1, v5
	v_permlane16_swap_b32_e32 v2, v6
	v_permlane16_swap_b32_e32 v3, v7
	v_permlane16_swap_b32_e32 v8, v12
	v_permlane16_swap_b32_e32 v9, v13
	v_permlane16_swap_b32_e32 v10, v14
	v_permlane16_swap_b32_e32 v11, v15
	v_permlane32_swap_b32_e32 v112, v116
	v_permlane32_swap_b32_e32 v113, v117
	v_permlane32_swap_b32_e32 v114, v118
	v_permlane32_swap_b32_e32 v115, v119
	v_permlane32_swap_b32_e32 v120, v124
	v_permlane32_swap_b32_e32 v121, v125
	v_permlane32_swap_b32_e32 v122, v126
	v_permlane32_swap_b32_e32 v123, v127
	v_permlane32_swap_b32_e32 v80, v84
	v_permlane32_swap_b32_e32 v81, v85
	v_permlane32_swap_b32_e32 v82, v86
	v_permlane32_swap_b32_e32 v83, v87
	v_permlane32_swap_b32_e32 v88, v92
	v_permlane32_swap_b32_e32 v89, v93
	v_permlane32_swap_b32_e32 v90, v94
	v_permlane32_swap_b32_e32 v91, v95
	v_permlane32_swap_b32_e32 v48, v52
	v_permlane32_swap_b32_e32 v49, v53
	v_permlane32_swap_b32_e32 v50, v54
	v_permlane32_swap_b32_e32 v51, v55
	v_permlane32_swap_b32_e32 v56, v60
	v_permlane32_swap_b32_e32 v57, v61
	v_permlane32_swap_b32_e32 v58, v62
	v_permlane32_swap_b32_e32 v59, v63
	v_permlane32_swap_b32_e32 v16, v20
	v_permlane32_swap_b32_e32 v17, v21
	v_permlane32_swap_b32_e32 v18, v22
	v_permlane32_swap_b32_e32 v19, v23
	v_permlane32_swap_b32_e32 v24, v28
	v_permlane32_swap_b32_e32 v25, v29
	v_permlane32_swap_b32_e32 v26, v30
	v_permlane32_swap_b32_e32 v27, v31
	v_permlane32_swap_b32_e32 v96, v100
	v_permlane32_swap_b32_e32 v97, v101
	v_permlane32_swap_b32_e32 v98, v102
	v_permlane32_swap_b32_e32 v99, v103
	v_permlane32_swap_b32_e32 v104, v108
	v_permlane32_swap_b32_e32 v105, v109
	v_permlane32_swap_b32_e32 v106, v110
	v_permlane32_swap_b32_e32 v107, v111
	v_permlane32_swap_b32_e32 v64, v68
	v_permlane32_swap_b32_e32 v65, v69
	v_permlane32_swap_b32_e32 v66, v70
	v_permlane32_swap_b32_e32 v67, v71
	v_permlane32_swap_b32_e32 v72, v76
	v_permlane32_swap_b32_e32 v73, v77
	v_permlane32_swap_b32_e32 v74, v78
	v_permlane32_swap_b32_e32 v75, v79
	v_permlane32_swap_b32_e32 v32, v36
	v_permlane32_swap_b32_e32 v33, v37
	v_permlane32_swap_b32_e32 v34, v38
	v_permlane32_swap_b32_e32 v35, v39
	v_permlane32_swap_b32_e32 v40, v44
	v_permlane32_swap_b32_e32 v41, v45
	v_permlane32_swap_b32_e32 v42, v46
	v_permlane32_swap_b32_e32 v43, v47
	v_permlane32_swap_b32_e32 v0, v4
	v_permlane32_swap_b32_e32 v1, v5
	v_permlane32_swap_b32_e32 v2, v6
	v_permlane32_swap_b32_e32 v3, v7
	v_permlane32_swap_b32_e32 v8, v12
	v_permlane32_swap_b32_e32 v9, v13
	v_permlane32_swap_b32_e32 v10, v14
	v_permlane32_swap_b32_e32 v11, v15
	v_lshl_add_u32 v247, v160, 8, v169
	v_and_or_b32 v246, v204, 31, v247
	v_ashrrev_i32_e32 v247, 31, v246
	v_lshl_add_u64 v[246:247], v[246:247], 2, s[44:45]
	global_load_dword v242, v[246:247], off
	global_load_dword v243, v[246:247], off offset:128
	global_load_dword v244, v[246:247], off offset:512
	global_load_dword v245, v[246:247], off offset:640
	s_and_saveexec_b64 s[6:7], vcc
	s_cbranch_execz .LBB0_91
	s_mov_b64 s[34:35], exec
	v_mbcnt_lo_u32_b32 v144, s34, 0
	v_mbcnt_hi_u32_b32 v144, s35, v144
	v_cmp_eq_u32_e64 s[38:39], 0, v144
	s_and_saveexec_b64 s[0:1], s[38:39]
	s_cbranch_execz .LBB0_90
	s_bcnt1_i32_b64 s9, s[34:35]
	v_mov_b32_e32 v145, s9
	global_atomic_add v145, v161, v145, s[30:31] offset:256 sc0

; __device__ __forceinline__ float sigm(float x) { return __builtin_amdgcn_rcpf(1.f + __builtin_amdgcn_exp2f(-LOG2E * x)); }
; __device__ __forceinline__ void epi_swiglu(const f32x16 (&acc)[2][2], int nbase, int tbase, int M, const float* ss, u16* ACT) {
;     ...
;     const int tok = tbase + tb * 32 + l32;
;     if (tok < M) {
;       const float rs = rsqrtf(ss[tok] * (1.f / 1024.f) + EPSN);
;       u16* dst = ACT + (size_t)tok * FFD + cb + 4 * h;
; #pragma unroll
;       for (int i = 0; i < 4; ++i) {
;         float o[4];
; #pragma unroll
;         for (int j = 0; j < 4; ++j) {
;           const float g = acc[0][tb][4 * i + j] * rs, u = acc[1][tb][4 * i + j] * rs;
;           o[j] = g * sigm(g) * u;
;         }
;         *(u32x2*)(dst + 8 * i) = (u32x2){pk_bf16(o[0], o[1]), pk_bf16(o[2], o[3])};
;       }
.LBB0_93:
	s_or_b64 exec, exec, s[6:7]
	v_mov_b32_e32 v146, v204
	s_load_dwordx2 s[0:1], s[64:65], 0x1c8
	v_lshl_or_b32 v144, v170, 7, v168
	v_lshl_add_u32 v155, v160, 8, v169
	v_ashrrev_i32_e32 v144, 1, v144
	v_and_or_b32 v148, v146, 31, v155
	v_ashrrev_i32_e32 v145, 31, v144
	v_lshrrev_b32_e32 v146, 2, v146
	s_waitcnt lgkmcnt(0)
	v_lshl_add_u64 v[144:145], v[144:145], 1, s[0:1]
	v_and_b32_e32 v160, 8, v146
	v_lshl_add_u64 v[146:147], v[144:145], 0, v[160:161]
	v_cmp_gt_i32_e64 s[40:41], s62, v148
	v_ashrrev_i32_e32 v149, 31, v148
	s_and_saveexec_b64 s[34:35], s[40:41]
	s_cbranch_execz .LBB0_95
	v_lshl_add_u64 v[150:151], v[148:149], 2, s[44:45]
	v_mov_b32_e32 v150, v242
	v_fmamk_f32 v150, v150, 0x3a800000, v205
	v_cmp_gt_f32_e64 s[40:41], s21, v150
	v_mul_f32_e32 v151, 0x4b800000, v150
	s_nop 0
	v_cndmask_b32_e64 v150, v150, v151, s[40:41]
	v_rsq_f32_e32 v150, v150
	s_nop 0
	v_mul_f32_e32 v151, 0x45800000, v150
	v_cndmask_b32_e64 v152, v150, v151, s[40:41]
	v_pk_mul_f32 v[112:113], v[112:113], v[152:153] op_sel_hi:[1,0]
	v_pk_mul_f32 v[96:97], v[96:97], v[152:153] op_sel_hi:[1,0]
	v_mul_f32_e32 v160, 0xbfb8aa3b, v112
	v_exp_f32_e32 v160, v160
	v_pk_mul_f32 v[98:99], v[98:99], v[152:153] op_sel_hi:[1,0]
	v_mad_i64_i32 v[150:151], s[0:1], v148, s56, v[146:147]
	v_add_f32_e32 v160, 1.0, v160
	v_rcp_f32_e32 v170, v160
	v_mul_f32_e32 v160, 0xbfb8aa3b, v113
	v_exp_f32_e32 v160, v160
	v_pk_mul_f32 v[100:101], v[100:101], v[152:153] op_sel_hi:[1,0]
	v_pk_mul_f32 v[102:103], v[102:103], v[152:153] op_sel_hi:[1,0]
	v_add_f32_e32 v160, 1.0, v160
	v_rcp_f32_e32 v171, v160
	s_nop 0
	v_pk_mul_f32 v[112:113], v[112:113], v[170:171]
	s_nop 0
	v_pk_mul_f32 v[96:97], v[96:97], v[112:113]
	v_pk_mul_f32 v[112:113], v[114:115], v[152:153] op_sel_hi:[1,0]
	v_cvt_pk_bf16_f32 v96, v96, v97
	v_mul_f32_e32 v114, 0xbfb8aa3b, v112
	v_mul_f32_e32 v115, 0xbfb8aa3b, v113
	v_exp_f32_e32 v114, v114
	v_exp_f32_e32 v115, v115
	v_add_f32_e32 v114, 1.0, v114
	v_add_f32_e32 v115, 1.0, v115
	v_rcp_f32_e32 v114, v114
	v_rcp_f32_e32 v115, v115
	s_nop 0
	v_pk_mul_f32 v[112:113], v[112:113], v[114:115]
	s_nop 0
	v_pk_mul_f32 v[98:99], v[98:99], v[112:113]
	s_nop 0
	v_cvt_pk_bf16_f32 v97, v98, v99
	v_mov_b32_e32 v222, v96
	v_mov_b32_e32 v223, v97
	v_pk_mul_f32 v[96:97], v[116:117], v[152:153] op_sel_hi:[1,0]
	s_nop 0
	v_mul_f32_e32 v98, 0xbfb8aa3b, v96
	v_mul_f32_e32 v99, 0xbfb8aa3b, v97
	v_exp_f32_e32 v98, v98
	v_exp_f32_e32 v99, v99
	v_add_f32_e32 v98, 1.0, v98
	v_add_f32_e32 v99, 1.0, v99
	v_rcp_f32_e32 v98, v98
	v_rcp_f32_e32 v99, v99
	s_nop 0
	v_pk_mul_f32 v[96:97], v[96:97], v[98:99]
	v_pk_mul_f32 v[98:99], v[118:119], v[152:153] op_sel_hi:[1,0]
	v_pk_mul_f32 v[96:97], v[100:101], v[96:97]
	v_mul_f32_e32 v100, 0xbfb8aa3b, v98
	v_mul_f32_e32 v101, 0xbfb8aa3b, v99
	v_exp_f32_e32 v100, v100
	v_exp_f32_e32 v101, v101
	v_cvt_pk_bf16_f32 v96, v96, v97
	v_add_f32_e32 v100, 1.0, v100
	v_add_f32_e32 v101, 1.0, v101
	v_rcp_f32_e32 v100, v100
	v_rcp_f32_e32 v101, v101
	s_nop 0
	v_pk_mul_f32 v[98:99], v[98:99], v[100:101]
	s_nop 0
	v_pk_mul_f32 v[98:99], v[102:103], v[98:99]
	v_pk_mul_f32 v[100:101], v[104:105], v[152:153] op_sel_hi:[1,0]
	v_cvt_pk_bf16_f32 v97, v98, v99
	v_mov_b32_e32 v224, v96
	v_mov_b32_e32 v225, v97
	v_lshrrev_b32_e32 v238, 2, v204
	v_and_b32_e32 v238, 8, v238
	v_mov_b32_e32 v239, 0
	v_lshl_add_u64 v[240:241], v[150:151], 0, v[238:239]
	v_permlane32_swap_b32_e32 v222, v224
	v_permlane32_swap_b32_e32 v223, v225
	global_store_dwordx4 v[240:241], v[222:225], off
	v_pk_mul_f32 v[96:97], v[120:121], v[152:153] op_sel_hi:[1,0]
	v_pk_mul_f32 v[102:103], v[106:107], v[152:153] op_sel_hi:[1,0]
	v_mul_f32_e32 v98, 0xbfb8aa3b, v96
	v_mul_f32_e32 v99, 0xbfb8aa3b, v97
	v_exp_f32_e32 v98, v98
	v_exp_f32_e32 v99, v99
	v_add_f32_e32 v98, 1.0, v98
	v_add_f32_e32 v99, 1.0, v99
	v_rcp_f32_e32 v98, v98
	v_rcp_f32_e32 v99, v99
	s_nop 0
	v_pk_mul_f32 v[96:97], v[96:97], v[98:99]
	v_pk_mul_f32 v[98:99], v[122:123], v[152:153] op_sel_hi:[1,0]
	v_pk_mul_f32 v[96:97], v[100:101], v[96:97]
	v_mul_f32_e32 v100, 0xbfb8aa3b, v98
	v_mul_f32_e32 v101, 0xbfb8aa3b, v99
	v_exp_f32_e32 v100, v100
	v_exp_f32_e32 v101, v101
	v_cvt_pk_bf16_f32 v96, v96, v97
	v_add_f32_e32 v100, 1.0, v100
	v_add_f32_e32 v101, 1.0, v101
	v_rcp_f32_e32 v100, v100
	v_rcp_f32_e32 v101, v101
	s_nop 0
	v_pk_mul_f32 v[98:99], v[98:99], v[100:101]
	s_nop 0
	v_pk_mul_f32 v[98:99], v[102:103], v[98:99]
	v_pk_mul_f32 v[100:101], v[108:109], v[152:153] op_sel_hi:[1,0]
	v_cvt_pk_bf16_f32 v97, v98, v99
	v_mov_b32_e32 v226, v96
	v_mov_b32_e32 v227, v97
	v_pk_mul_f32 v[96:97], v[124:125], v[152:153] op_sel_hi:[1,0]
	v_pk_mul_f32 v[102:103], v[110:111], v[152:153] op_sel_hi:[1,0]
	v_mul_f32_e32 v98, 0xbfb8aa3b, v96
	v_mul_f32_e32 v99, 0xbfb8aa3b, v97
	v_exp_f32_e32 v98, v98
	v_exp_f32_e32 v99, v99
	v_add_f32_e32 v98, 1.0, v98
	v_add_f32_e32 v99, 1.0, v99
	v_rcp_f32_e32 v98, v98
	v_rcp_f32_e32 v99, v99
	s_nop 0
	v_pk_mul_f32 v[96:97], v[96:97], v[98:99]
	v_pk_mul_f32 v[98:99], v[126:127], v[152:153] op_sel_hi:[1,0]
	v_pk_mul_f32 v[96:97], v[100:101], v[96:97]
	v_mul_f32_e32 v100, 0xbfb8aa3b, v98
	v_mul_f32_e32 v101, 0xbfb8aa3b, v99
	v_exp_f32_e32 v100, v100
	v_exp_f32_e32 v101, v101
	v_cvt_pk_bf16_f32 v96, v96, v97
	v_add_f32_e32 v100, 1.0, v100
	v_add_f32_e32 v101, 1.0, v101
	v_rcp_f32_e32 v100, v100
	v_rcp_f32_e32 v101, v101
	s_nop 0
	v_pk_mul_f32 v[98:99], v[98:99], v[100:101]
	s_nop 0
	v_pk_mul_f32 v[98:99], v[102:103], v[98:99]
	s_nop 0
	v_cvt_pk_bf16_f32 v97, v98, v99
	v_mov_b32_e32 v228, v96
	v_mov_b32_e32 v229, v97
	s_nop 1
	v_permlane32_swap_b32_e32 v226, v228
	v_permlane32_swap_b32_e32 v227, v229
	global_store_dwordx4 v[240:241], v[226:229], off offset:32

; __device__ __forceinline__ void h_main(f32x16 (&acc0)[2][2], f32x16 (&acc1)[2][2], const WideCtx& c, int nk, char* lds) {
;   const int h = c.h;
;   for (int kt = 0; kt < nk; ++kt) {
;     asm volatile("s_waitcnt vmcnt(0)" ::: "memory");
;     __builtin_amdgcn_s_barrier();
;     if (kt + 1 < nk) h_stage(c, kt + 1);
;     const char* st = lds + (kt & 1) * 24576;
; #pragma unroll
;     for (int ks = 0; ks < 2; ++ks) {
;       bf16x8 wf[2], a0[2], a1[2];
; #pragma unroll
;       for (int b = 0; b < 2; ++b) {
;         wf[b] = *(const bf16x8*)(st + c.wro[b] + (((ks * 2 + h) ^ c.wsw[b]) << 4));
;         a0[b] = *(const bf16x8*)(st + c.aro[0][b] + (((ks * 2 + h) ^ c.asw[0][b]) << 4));
;         a1[b] = *(const bf16x8*)(st + c.aro[1][b] + (((ks * 2 + h) ^ c.asw[1][b]) << 4));
;       }
; #pragma unroll
;       for (int nb = 0; nb < 2; ++nb)
; #pragma unroll
;         for (int tb = 0; tb < 2; ++tb) {
;           acc0[nb][tb] = __builtin_amdgcn_mfma_f32_32x32x16_bf16(wf[nb], a0[tb], acc0[nb][tb], 0, 0, 0);
;           acc1[nb][tb] = __builtin_amdgcn_mfma_f32_32x32x16_bf16(wf[nb], a1[tb], acc1[nb][tb], 0, 0, 0);
;         }
;     }
;   }
; }
.LBB0_616:
	s_waitcnt vmcnt(6)
	s_barrier
	v_add_u32_e32 v171, s6, v248
	v_add_u32_e32 v196, s6, v249
	ds_read_b128 v[172:175], v171
	ds_read_b128 v[176:179], v196 offset:8192
	ds_read_b128 v[188:191], v196 offset:9216
	ds_read_b128 v[180:183], v196 offset:10240
	ds_read_b128 v[192:195], v196 offset:11264
	ds_read_b128 v[230:233], v196 offset:16384
	ds_read_b128 v[234:237], v196 offset:17408
	ds_read_b128 v[238:241], v196 offset:18432
	ds_read_b128 v[242:245], v196 offset:19456
	ds_read_b128 v[184:187], v171 offset:1024
	ds_read_b128 v[222:225], v171 offset:2048
	ds_read_b128 v[226:229], v171 offset:3072
	s_add_i32 s7, s6, 0xffffa000
	s_cmp_eq_u32 s6, 0
	s_cselect_b32 s7, 0xc000, s7
	s_add_i32 m0, s7, s24
	s_add_i32 s7, s6, 0x6000
	global_load_lds_dwordx4 v154, s[0:1]
	s_add_i32 m0, m0, 0x1000
	s_cmp_eq_u32 s6, 0xc000
	global_load_lds_dwordx4 v152, s[0:1]
	s_cselect_b32 s6, 0, s7
	s_add_i32 m0, m0, 0x1000
	s_waitcnt lgkmcnt(10)
	v_mfma_f32_16x16x32_bf16 v[112:115], v[172:175], v[176:179], v[112:115]
	global_load_lds_dwordx4 v150, s[0:1]
	s_add_i32 m0, m0, 0x1000
	s_waitcnt lgkmcnt(9)
	v_mfma_f32_16x16x32_bf16 v[116:119], v[172:175], v[188:191], v[116:119]
	global_load_lds_dwordx4 v148, s[0:1]
	s_add_i32 m0, m0, 0x1000
	s_waitcnt lgkmcnt(8)
	v_mfma_f32_16x16x32_bf16 v[80:83], v[172:175], v[180:183], v[80:83]
	global_load_lds_dwordx4 v146, s[0:1]
	s_add_i32 m0, m0, 0x1000
	s_waitcnt lgkmcnt(7)
	v_mfma_f32_16x16x32_bf16 v[84:87], v[172:175], v[192:195], v[84:87]
	global_load_lds_dwordx4 v144, s[0:1]
	s_add_u32 s0, s0, 64
	s_addc_u32 s1, s1, 0
	s_waitcnt lgkmcnt(6)
	v_mfma_f32_16x16x32_bf16 v[48:51], v[172:175], v[230:233], v[48:51]
	s_waitcnt lgkmcnt(5)
	v_mfma_f32_16x16x32_bf16 v[52:55], v[172:175], v[234:237], v[52:55]
	s_waitcnt lgkmcnt(4)
	v_mfma_f32_16x16x32_bf16 v[16:19], v[172:175], v[238:241], v[16:19]
	s_waitcnt lgkmcnt(3)
	v_mfma_f32_16x16x32_bf16 v[20:23], v[172:175], v[242:245], v[20:23]
	s_waitcnt lgkmcnt(2)
	v_mfma_f32_16x16x32_bf16 v[120:123], v[184:187], v[176:179], v[120:123]
	v_mfma_f32_16x16x32_bf16 v[124:127], v[184:187], v[188:191], v[124:127]
	v_mfma_f32_16x16x32_bf16 v[88:91], v[184:187], v[180:183], v[88:91]
	v_mfma_f32_16x16x32_bf16 v[92:95], v[184:187], v[192:195], v[92:95]
	v_mfma_f32_16x16x32_bf16 v[56:59], v[184:187], v[230:233], v[56:59]
	v_mfma_f32_16x16x32_bf16 v[60:63], v[184:187], v[234:237], v[60:63]
	v_mfma_f32_16x16x32_bf16 v[24:27], v[184:187], v[238:241], v[24:27]
	v_mfma_f32_16x16x32_bf16 v[28:31], v[184:187], v[242:245], v[28:31]
	s_waitcnt lgkmcnt(1)
	v_mfma_f32_16x16x32_bf16 v[96:99], v[222:225], v[176:179], v[96:99]
	v_mfma_f32_16x16x32_bf16 v[100:103], v[222:225], v[188:191], v[100:103]
	v_mfma_f32_16x16x32_bf16 v[64:67], v[222:225], v[180:183], v[64:67]
	v_mfma_f32_16x16x32_bf16 v[68:71], v[222:225], v[192:195], v[68:71]
	v_mfma_f32_16x16x32_bf16 v[32:35], v[222:225], v[230:233], v[32:35]
	v_mfma_f32_16x16x32_bf16 v[36:39], v[222:225], v[234:237], v[36:39]
	v_mfma_f32_16x16x32_bf16 v[0:3], v[222:225], v[238:241], v[0:3]
	v_mfma_f32_16x16x32_bf16 v[4:7], v[222:225], v[242:245], v[4:7]
	s_waitcnt lgkmcnt(0)
	v_mfma_f32_16x16x32_bf16 v[104:107], v[226:229], v[176:179], v[104:107]
	v_mfma_f32_16x16x32_bf16 v[108:111], v[226:229], v[188:191], v[108:111]
	v_mfma_f32_16x16x32_bf16 v[72:75], v[226:229], v[180:183], v[72:75]
	v_mfma_f32_16x16x32_bf16 v[76:79], v[226:229], v[192:195], v[76:79]
	v_mfma_f32_16x16x32_bf16 v[40:43], v[226:229], v[230:233], v[40:43]
	v_mfma_f32_16x16x32_bf16 v[44:47], v[226:229], v[234:237], v[44:47]
	v_mfma_f32_16x16x32_bf16 v[8:11], v[226:229], v[238:241], v[8:11]
	v_mfma_f32_16x16x32_bf16 v[12:15], v[226:229], v[242:245], v[12:15]
	s_add_i32 s9, s9, 1
	s_cmp_eq_u32 s9, 32
	s_cbranch_scc0 .LBB0_616
	s_waitcnt vmcnt(6)
	s_barrier
	v_add_u32_e32 v171, s6, v248
	v_add_u32_e32 v196, s6, v249
	ds_read_b128 v[172:175], v171
	ds_read_b128 v[176:179], v196 offset:8192
	ds_read_b128 v[188:191], v196 offset:9216
	ds_read_b128 v[180:183], v196 offset:10240
	ds_read_b128 v[192:195], v196 offset:11264
	ds_read_b128 v[230:233], v196 offset:16384
	ds_read_b128 v[234:237], v196 offset:17408
	ds_read_b128 v[238:241], v196 offset:18432
	ds_read_b128 v[242:245], v196 offset:19456
	ds_read_b128 v[184:187], v171 offset:1024
	ds_read_b128 v[222:225], v171 offset:2048
	ds_read_b128 v[226:229], v171 offset:3072
	s_add_i32 s7, s6, 0x6000
	s_cmp_eq_u32 s6, 0xc000
	s_cselect_b32 s6, 0, s7
	s_waitcnt lgkmcnt(10)
	v_mfma_f32_16x16x32_bf16 v[112:115], v[172:175], v[176:179], v[112:115]
	s_waitcnt lgkmcnt(9)
	v_mfma_f32_16x16x32_bf16 v[116:119], v[172:175], v[188:191], v[116:119]
	s_waitcnt lgkmcnt(8)
	v_mfma_f32_16x16x32_bf16 v[80:83], v[172:175], v[180:183], v[80:83]
	s_waitcnt lgkmcnt(7)
	v_mfma_f32_16x16x32_bf16 v[84:87], v[172:175], v[192:195], v[84:87]
	s_waitcnt lgkmcnt(6)
	v_mfma_f32_16x16x32_bf16 v[48:51], v[172:175], v[230:233], v[48:51]
	s_waitcnt lgkmcnt(5)
	v_mfma_f32_16x16x32_bf16 v[52:55], v[172:175], v[234:237], v[52:55]
	s_waitcnt lgkmcnt(4)
	v_mfma_f32_16x16x32_bf16 v[16:19], v[172:175], v[238:241], v[16:19]
	s_waitcnt lgkmcnt(3)
	v_mfma_f32_16x16x32_bf16 v[20:23], v[172:175], v[242:245], v[20:23]
	s_waitcnt lgkmcnt(2)
	v_mfma_f32_16x16x32_bf16 v[120:123], v[184:187], v[176:179], v[120:123]
	v_mfma_f32_16x16x32_bf16 v[124:127], v[184:187], v[188:191], v[124:127]
	v_mfma_f32_16x16x32_bf16 v[88:91], v[184:187], v[180:183], v[88:91]
	v_mfma_f32_16x16x32_bf16 v[92:95], v[184:187], v[192:195], v[92:95]
	v_mfma_f32_16x16x32_bf16 v[56:59], v[184:187], v[230:233], v[56:59]
	v_mfma_f32_16x16x32_bf16 v[60:63], v[184:187], v[234:237], v[60:63]
	v_mfma_f32_16x16x32_bf16 v[24:27], v[184:187], v[238:241], v[24:27]
	v_mfma_f32_16x16x32_bf16 v[28:31], v[184:187], v[242:245], v[28:31]
	s_waitcnt lgkmcnt(1)
	v_mfma_f32_16x16x32_bf16 v[96:99], v[222:225], v[176:179], v[96:99]
	v_mfma_f32_16x16x32_bf16 v[100:103], v[222:225], v[188:191], v[100:103]
	v_mfma_f32_16x16x32_bf16 v[64:67], v[222:225], v[180:183], v[64:67]
	v_mfma_f32_16x16x32_bf16 v[68:71], v[222:225], v[192:195], v[68:71]
	v_mfma_f32_16x16x32_bf16 v[32:35], v[222:225], v[230:233], v[32:35]
	v_mfma_f32_16x16x32_bf16 v[36:39], v[222:225], v[234:237], v[36:39]
	v_mfma_f32_16x16x32_bf16 v[0:3], v[222:225], v[238:241], v[0:3]
	v_mfma_f32_16x16x32_bf16 v[4:7], v[222:225], v[242:245], v[4:7]
	s_waitcnt lgkmcnt(0)
	v_mfma_f32_16x16x32_bf16 v[104:107], v[226:229], v[176:179], v[104:107]
	v_mfma_f32_16x16x32_bf16 v[108:111], v[226:229], v[188:191], v[108:111]
	v_mfma_f32_16x16x32_bf16 v[72:75], v[226:229], v[180:183], v[72:75]
	v_mfma_f32_16x16x32_bf16 v[76:79], v[226:229], v[192:195], v[76:79]
	v_mfma_f32_16x16x32_bf16 v[40:43], v[226:229], v[230:233], v[40:43]
	v_mfma_f32_16x16x32_bf16 v[44:47], v[226:229], v[234:237], v[44:47]
	v_mfma_f32_16x16x32_bf16 v[8:11], v[226:229], v[238:241], v[8:11]
	v_mfma_f32_16x16x32_bf16 v[12:15], v[226:229], v[242:245], v[12:15]
	s_waitcnt vmcnt(0)
	s_barrier
; __device__ __forceinline__ void h_main(f32x16 (&acc0)[2][2], f32x16 (&acc1)[2][2], const WideCtx& c, int nk, char* lds) {
;   const int h = c.h;
;   for (int kt = 0; kt < nk; ++kt) {
;     asm volatile("s_waitcnt vmcnt(0)" ::: "memory");
;     __builtin_amdgcn_s_barrier();
;     if (kt + 1 < nk) h_stage(c, kt + 1);
;     const char* st = lds + (kt & 1) * 24576;
; #pragma unroll
;     for (int ks = 0; ks < 2; ++ks) {
;       bf16x8 wf[2], a0[2], a1[2];
; #pragma unroll
;       for (int b = 0; b < 2; ++b) {
;         wf[b] = *(const bf16x8*)(st + c.wro[b] + (((ks * 2 + h) ^ c.wsw[b]) << 4));
;         a0[b] = *(const bf16x8*)(st + c.aro[0][b] + (((ks * 2 + h) ^ c.asw[0][b]) << 4));
;         a1[b] = *(const bf16x8*)(st + c.aro[1][b] + (((ks * 2 + h) ^ c.asw[1][b]) << 4));
;       }
; #pragma unroll
;       for (int nb = 0; nb < 2; ++nb)
; #pragma unroll
;         for (int tb = 0; tb < 2; ++tb) {
;           acc0[nb][tb] = __builtin_amdgcn_mfma_f32_32x32x16_bf16(wf[nb], a0[tb], acc0[nb][tb], 0, 0, 0);
;           acc1[nb][tb] = __builtin_amdgcn_mfma_f32_32x32x16_bf16(wf[nb], a1[tb], acc1[nb][tb], 0, 0, 0);
;         }
;     }
;   }
; }
	v_add_u32_e32 v171, s6, v248
	v_add_u32_e32 v196, s6, v249
	ds_read_b128 v[172:175], v171
	ds_read_b128 v[176:179], v196 offset:8192
	ds_read_b128 v[188:191], v196 offset:9216
	ds_read_b128 v[180:183], v196 offset:10240
	ds_read_b128 v[192:195], v196 offset:11264
	ds_read_b128 v[230:233], v196 offset:16384
	ds_read_b128 v[234:237], v196 offset:17408
	ds_read_b128 v[238:241], v196 offset:18432
	ds_read_b128 v[242:245], v196 offset:19456
	ds_read_b128 v[184:187], v171 offset:1024
	ds_read_b128 v[222:225], v171 offset:2048
	ds_read_b128 v[226:229], v171 offset:3072
	s_add_i32 s7, s6, 0x6000
	s_cmp_eq_u32 s6, 0xc000
	s_cselect_b32 s6, 0, s7
	s_waitcnt lgkmcnt(10)
	v_mfma_f32_16x16x32_bf16 v[112:115], v[172:175], v[176:179], v[112:115]
	s_waitcnt lgkmcnt(9)
	v_mfma_f32_16x16x32_bf16 v[116:119], v[172:175], v[188:191], v[116:119]
	s_waitcnt lgkmcnt(8)
	v_mfma_f32_16x16x32_bf16 v[80:83], v[172:175], v[180:183], v[80:83]
	s_waitcnt lgkmcnt(7)
	v_mfma_f32_16x16x32_bf16 v[84:87], v[172:175], v[192:195], v[84:87]
	s_waitcnt lgkmcnt(6)
	v_mfma_f32_16x16x32_bf16 v[48:51], v[172:175], v[230:233], v[48:51]
	s_waitcnt lgkmcnt(5)
	v_mfma_f32_16x16x32_bf16 v[52:55], v[172:175], v[234:237], v[52:55]
	s_waitcnt lgkmcnt(4)
	v_mfma_f32_16x16x32_bf16 v[16:19], v[172:175], v[238:241], v[16:19]
	s_waitcnt lgkmcnt(3)
	v_mfma_f32_16x16x32_bf16 v[20:23], v[172:175], v[242:245], v[20:23]
	s_waitcnt lgkmcnt(2)
	v_mfma_f32_16x16x32_bf16 v[120:123], v[184:187], v[176:179], v[120:123]
	v_mfma_f32_16x16x32_bf16 v[124:127], v[184:187], v[188:191], v[124:127]
	v_mfma_f32_16x16x32_bf16 v[88:91], v[184:187], v[180:183], v[88:91]
	v_mfma_f32_16x16x32_bf16 v[92:95], v[184:187], v[192:195], v[92:95]
	v_mfma_f32_16x16x32_bf16 v[56:59], v[184:187], v[230:233], v[56:59]
	v_mfma_f32_16x16x32_bf16 v[60:63], v[184:187], v[234:237], v[60:63]
	v_mfma_f32_16x16x32_bf16 v[24:27], v[184:187], v[238:241], v[24:27]
	v_mfma_f32_16x16x32_bf16 v[28:31], v[184:187], v[242:245], v[28:31]
	s_waitcnt lgkmcnt(1)
	v_mfma_f32_16x16x32_bf16 v[96:99], v[222:225], v[176:179], v[96:99]
	v_mfma_f32_16x16x32_bf16 v[100:103], v[222:225], v[188:191], v[100:103]
	v_mfma_f32_16x16x32_bf16 v[64:67], v[222:225], v[180:183], v[64:67]
	v_mfma_f32_16x16x32_bf16 v[68:71], v[222:225], v[192:195], v[68:71]
	v_mfma_f32_16x16x32_bf16 v[32:35], v[222:225], v[230:233], v[32:35]
	v_mfma_f32_16x16x32_bf16 v[36:39], v[222:225], v[234:237], v[36:39]
	v_mfma_f32_16x16x32_bf16 v[0:3], v[222:225], v[238:241], v[0:3]
	v_mfma_f32_16x16x32_bf16 v[4:7], v[222:225], v[242:245], v[4:7]
	s_waitcnt lgkmcnt(0)
; __device__ __forceinline__ void h_main(f32x16 (&acc0)[2][2], f32x16 (&acc1)[2][2], const WideCtx& c, int nk, char* lds) {
;     ...
;           acc0[nb][tb] = __builtin_amdgcn_mfma_f32_32x32x16_bf16(wf[nb], a0[tb], acc0[nb][tb], 0, 0, 0);
;           acc1[nb][tb] = __builtin_amdgcn_mfma_f32_32x32x16_bf16(wf[nb], a1[tb], acc1[nb][tb], 0, 0, 0);
; template <class F>
; __device__ __forceinline__ void gemm_phase_w(const u16* A, int lda, int M, const u16* W, int K, int N, char* lds, int* ctr, F&& epi) {
;     ...
;     const int ctm = tm, ctn = tn;
;     par ^= 1;
;     if (c.tid == 0) bw[2 + par] = atomicAdd(myctr, 1);
	v_mfma_f32_16x16x32_bf16 v[104:107], v[226:229], v[176:179], v[104:107]
	v_mfma_f32_16x16x32_bf16 v[108:111], v[226:229], v[188:191], v[108:111]
	v_mfma_f32_16x16x32_bf16 v[72:75], v[226:229], v[180:183], v[72:75]
	v_mfma_f32_16x16x32_bf16 v[76:79], v[226:229], v[192:195], v[76:79]
	v_mfma_f32_16x16x32_bf16 v[40:43], v[226:229], v[230:233], v[40:43]
	v_mfma_f32_16x16x32_bf16 v[44:47], v[226:229], v[234:237], v[44:47]
	v_mfma_f32_16x16x32_bf16 v[8:11], v[226:229], v[238:241], v[8:11]
	v_mfma_f32_16x16x32_bf16 v[12:15], v[226:229], v[242:245], v[12:15]
	s_xor_b32 s9, s9, 1
	s_nop 7
	s_nop 7
	v_permlane16_swap_b32_e32 v112, v116
	v_permlane16_swap_b32_e32 v113, v117
	v_permlane16_swap_b32_e32 v114, v118
	v_permlane16_swap_b32_e32 v115, v119
	v_permlane16_swap_b32_e32 v120, v124
	v_permlane16_swap_b32_e32 v121, v125
	v_permlane16_swap_b32_e32 v122, v126
	v_permlane16_swap_b32_e32 v123, v127
	v_permlane16_swap_b32_e32 v80, v84
	v_permlane16_swap_b32_e32 v81, v85
	v_permlane16_swap_b32_e32 v82, v86
	v_permlane16_swap_b32_e32 v83, v87
	v_permlane16_swap_b32_e32 v88, v92
	v_permlane16_swap_b32_e32 v89, v93
	v_permlane16_swap_b32_e32 v90, v94
	v_permlane16_swap_b32_e32 v91, v95
	v_permlane16_swap_b32_e32 v48, v52
	v_permlane16_swap_b32_e32 v49, v53
	v_permlane16_swap_b32_e32 v50, v54
	v_permlane16_swap_b32_e32 v51, v55
	v_permlane16_swap_b32_e32 v56, v60
	v_permlane16_swap_b32_e32 v57, v61
	v_permlane16_swap_b32_e32 v58, v62
	v_permlane16_swap_b32_e32 v59, v63
	v_permlane16_swap_b32_e32 v16, v20
	v_permlane16_swap_b32_e32 v17, v21
	v_permlane16_swap_b32_e32 v18, v22
	v_permlane16_swap_b32_e32 v19, v23
	v_permlane16_swap_b32_e32 v24, v28
	v_permlane16_swap_b32_e32 v25, v29
	v_permlane16_swap_b32_e32 v26, v30
	v_permlane16_swap_b32_e32 v27, v31
	v_permlane16_swap_b32_e32 v96, v100
	v_permlane16_swap_b32_e32 v97, v101
	v_permlane16_swap_b32_e32 v98, v102
	v_permlane16_swap_b32_e32 v99, v103
	v_permlane16_swap_b32_e32 v104, v108
	v_permlane16_swap_b32_e32 v105, v109
	v_permlane16_swap_b32_e32 v106, v110
	v_permlane16_swap_b32_e32 v107, v111
	v_permlane16_swap_b32_e32 v64, v68
	v_permlane16_swap_b32_e32 v65, v69
	v_permlane16_swap_b32_e32 v66, v70
	v_permlane16_swap_b32_e32 v67, v71
	v_permlane16_swap_b32_e32 v72, v76
	v_permlane16_swap_b32_e32 v73, v77
	v_permlane16_swap_b32_e32 v74, v78
	v_permlane16_swap_b32_e32 v75, v79
	v_permlane16_swap_b32_e32 v32, v36
	v_permlane16_swap_b32_e32 v33, v37
	v_permlane16_swap_b32_e32 v34, v38
	v_permlane16_swap_b32_e32 v35, v39
	v_permlane16_swap_b32_e32 v40, v44
	v_permlane16_swap_b32_e32 v41, v45
	v_permlane16_swap_b32_e32 v42, v46
	v_permlane16_swap_b32_e32 v43, v47
	v_permlane16_swap_b32_e32 v0, v4
	v_permlane16_swap_b32_e32 v1, v5
	v_permlane16_swap_b32_e32 v2, v6
	v_permlane16_swap_b32_e32 v3, v7
	v_permlane16_swap_b32_e32 v8, v12
	v_permlane16_swap_b32_e32 v9, v13
	v_permlane16_swap_b32_e32 v10, v14
	v_permlane16_swap_b32_e32 v11, v15
	v_permlane32_swap_b32_e32 v112, v116
	v_permlane32_swap_b32_e32 v113, v117
	v_permlane32_swap_b32_e32 v114, v118
	v_permlane32_swap_b32_e32 v115, v119
	v_permlane32_swap_b32_e32 v120, v124
	v_permlane32_swap_b32_e32 v121, v125
	v_permlane32_swap_b32_e32 v122, v126
	v_permlane32_swap_b32_e32 v123, v127
	v_permlane32_swap_b32_e32 v80, v84
	v_permlane32_swap_b32_e32 v81, v85
	v_permlane32_swap_b32_e32 v82, v86
	v_permlane32_swap_b32_e32 v83, v87
	v_permlane32_swap_b32_e32 v88, v92
	v_permlane32_swap_b32_e32 v89, v93
	v_permlane32_swap_b32_e32 v90, v94
	v_permlane32_swap_b32_e32 v91, v95
	v_permlane32_swap_b32_e32 v48, v52
	v_permlane32_swap_b32_e32 v49, v53
	v_permlane32_swap_b32_e32 v50, v54
	v_permlane32_swap_b32_e32 v51, v55
	v_permlane32_swap_b32_e32 v56, v60
	v_permlane32_swap_b32_e32 v57, v61
	v_permlane32_swap_b32_e32 v58, v62
	v_permlane32_swap_b32_e32 v59, v63
	v_permlane32_swap_b32_e32 v16, v20
	v_permlane32_swap_b32_e32 v17, v21
	v_permlane32_swap_b32_e32 v18, v22
	v_permlane32_swap_b32_e32 v19, v23
	v_permlane32_swap_b32_e32 v24, v28
	v_permlane32_swap_b32_e32 v25, v29
	v_permlane32_swap_b32_e32 v26, v30
	v_permlane32_swap_b32_e32 v27, v31
	v_permlane32_swap_b32_e32 v96, v100
	v_permlane32_swap_b32_e32 v97, v101
	v_permlane32_swap_b32_e32 v98, v102
	v_permlane32_swap_b32_e32 v99, v103
	v_permlane32_swap_b32_e32 v104, v108
	v_permlane32_swap_b32_e32 v105, v109
	v_permlane32_swap_b32_e32 v106, v110
	v_permlane32_swap_b32_e32 v107, v111
	v_permlane32_swap_b32_e32 v64, v68
	v_permlane32_swap_b32_e32 v65, v69
	v_permlane32_swap_b32_e32 v66, v70
	v_permlane32_swap_b32_e32 v67, v71
	v_permlane32_swap_b32_e32 v72, v76
	v_permlane32_swap_b32_e32 v73, v77
	v_permlane32_swap_b32_e32 v74, v78
	v_permlane32_swap_b32_e32 v75, v79
	v_permlane32_swap_b32_e32 v32, v36
	v_permlane32_swap_b32_e32 v33, v37
	v_permlane32_swap_b32_e32 v34, v38
	v_permlane32_swap_b32_e32 v35, v39
	v_permlane32_swap_b32_e32 v40, v44
	v_permlane32_swap_b32_e32 v41, v45
	v_permlane32_swap_b32_e32 v42, v46
	v_permlane32_swap_b32_e32 v43, v47
	v_permlane32_swap_b32_e32 v0, v4
	v_permlane32_swap_b32_e32 v1, v5
	v_permlane32_swap_b32_e32 v2, v6
	v_permlane32_swap_b32_e32 v3, v7
	v_permlane32_swap_b32_e32 v8, v12
	v_permlane32_swap_b32_e32 v9, v13
	v_permlane32_swap_b32_e32 v10, v14
	v_permlane32_swap_b32_e32 v11, v15
	v_lshl_add_u32 v247, v170, 8, v169
	v_and_or_b32 v246, v204, 31, v247
	v_ashrrev_i32_e32 v247, 31, v246
	v_lshl_add_u64 v[246:247], v[246:247], 2, s[48:49]
	global_load_dword v242, v[246:247], off
	global_load_dword v243, v[246:247], off offset:128
	global_load_dword v244, v[246:247], off offset:512
	global_load_dword v245, v[246:247], off offset:640
	s_and_saveexec_b64 s[6:7], vcc
	s_cbranch_execz .LBB0_621
	s_mov_b64 s[34:35], exec
	v_mbcnt_lo_u32_b32 v144, s34, 0
	v_mbcnt_hi_u32_b32 v144, s35, v144
	v_cmp_eq_u32_e64 s[38:39], 0, v144
	s_and_saveexec_b64 s[0:1], s[38:39]
	s_cbranch_execz .LBB0_620
	s_bcnt1_i32_b64 s34, s[34:35]
	v_mov_b32_e32 v145, s34
	global_atomic_add v145, v161, v145, s[30:31] offset:256 sc0

; __device__ __forceinline__ u16 bf16_1(float a) { return (u16)(pk_bf16(a, 0.f) & 0xffffu); }
; __device__ void run_phase(CP& p, int ph, char* lds) {
;     ...
;           const int tok = tbase + tb * 32 + l32;
;           if (tok < M) {
;             const float rs = rsqrtf(p.ss1[tok] * (1.f / 1024.f) + EPSN);
;             if (!G.meta && nbase >= 2048 && nbase < 3072) {
;               const int s = tok >> G.lgS, t = 16 + (tok & (G.S - 1));
;               const int Lp = (G.L + 63) & ~63;
;               const int pos = (t & ~12) | ((t & 4) << 1) | ((t & 8) >> 1);
;               u16* vt = p.VT + ((size_t)(s * 1024 + (nbase - 2048)) * Lp) + pos;
; #pragma unroll
;               for (int nb = 0; nb < 2; ++nb)
; #pragma unroll
;                 for (int r = 0; r < 16; ++r) {
;                   const int dvl = nb * 32 + 8 * (r >> 2) + 4 * h + (r & 3);
;                   vt[(size_t)dvl * Lp] = bf16_1(acc[nb][tb][r] * rs);
;                 }
;             } else {
;               u16* dst = Pout + (size_t)tok * NIN + nbase + 4 * h;
; #pragma unroll
;               for (int nb = 0; nb < 2; ++nb)
; #pragma unroll
;                 for (int i = 0; i < 4; ++i)
;                   *(u32x2*)(dst + nb * 32 + 8 * i) = (u32x2){pk_bf16(acc[nb][tb][4 * i] * rs, acc[nb][tb][4 * i + 1] * rs),
;                                                              pk_bf16(acc[nb][tb][4 * i + 2] * rs, acc[nb][tb][4 * i + 3] * rs)};
;             }
.LBB0_623:
	s_or_b64 exec, exec, s[6:7]
	v_mov_b32_e32 v147, v204
	v_lshl_add_u32 v154, v170, 8, v169
	v_lshl_or_b32 v144, v160, 7, v168
	v_and_or_b32 v146, v147, 31, v154
	v_and_b32_e32 v145, 0x1fffff8, v160
	v_lshrrev_b32_e32 v147, 3, v147
	v_cmp_eq_u32_e64 s[40:41], 16, v145
	v_ashrrev_i32_e32 v145, 31, v144
	v_and_b32_e32 v155, 4, v147
	v_add_u32_e32 v153, 0xfffff800, v144
	v_cmp_gt_i32_e64 s[42:43], s62, v146
	v_ashrrev_i32_e32 v147, 31, v146
	s_and_saveexec_b64 s[34:35], s[42:43]
	s_cbranch_execz .LBB0_628
	v_lshl_add_u64 v[150:151], v[146:147], 2, s[48:49]
	s_and_b64 s[0:1], s[86:87], s[40:41]
	s_xor_b64 s[0:1], s[0:1], -1
	v_mov_b32_e32 v148, v242
	v_fmamk_f32 v148, v148, 0x3a800000, v205
	v_mul_f32_e32 v150, 0x4b800000, v148
	v_cmp_gt_f32_e64 s[42:43], s21, v148
	s_nop 1
	v_cndmask_b32_e64 v148, v148, v150, s[42:43]
	v_rsq_f32_e32 v148, v148
	s_nop 0
	v_mul_f32_e32 v150, 0x45800000, v148
	v_cndmask_b32_e64 v148, v148, v150, s[42:43]
	s_and_saveexec_b64 s[6:7], s[0:1]
	s_xor_b64 s[6:7], exec, s[6:7]
	s_cbranch_execz .LBB0_626
	v_mov_b64_e32 v[150:151], s[46:47]
	v_mad_i64_i32 v[150:151], s[0:1], v146, s74, v[150:151]
	v_lshl_add_u64 v[150:151], v[144:145], 1, v[150:151]
	v_lshlrev_b32_e32 v160, 1, v155
	v_lshl_add_u64 v[150:151], v[150:151], 0, v[160:161]
	v_lshl_add_u64 v[150:151], v[150:151], 0, v[160:161]
	v_pk_mul_f32 v[112:113], v[112:113], v[148:149] op_sel_hi:[1,0]
	v_pk_mul_f32 v[114:115], v[114:115], v[148:149] op_sel_hi:[1,0]
	v_pk_mul_f32 v[116:117], v[116:117], v[148:149] op_sel_hi:[1,0]
	v_pk_mul_f32 v[118:119], v[118:119], v[148:149] op_sel_hi:[1,0]
	v_cvt_pk_bf16_f32 v222, v112, v113
	v_cvt_pk_bf16_f32 v223, v114, v115
	v_cvt_pk_bf16_f32 v224, v116, v117
	v_cvt_pk_bf16_f32 v225, v118, v119
	s_nop 1
	v_permlane32_swap_b32_e32 v222, v224
	v_permlane32_swap_b32_e32 v223, v225
	global_store_dwordx4 v[150:151], v[222:225], off
	v_pk_mul_f32 v[120:121], v[120:121], v[148:149] op_sel_hi:[1,0]
	v_pk_mul_f32 v[122:123], v[122:123], v[148:149] op_sel_hi:[1,0]
	v_pk_mul_f32 v[124:125], v[124:125], v[148:149] op_sel_hi:[1,0]
	v_pk_mul_f32 v[126:127], v[126:127], v[148:149] op_sel_hi:[1,0]
	v_cvt_pk_bf16_f32 v226, v120, v121
	v_cvt_pk_bf16_f32 v227, v122, v123
	v_cvt_pk_bf16_f32 v228, v124, v125
	v_cvt_pk_bf16_f32 v229, v126, v127
	s_nop 1
	v_permlane32_swap_b32_e32 v226, v228
	v_permlane32_swap_b32_e32 v227, v229
	global_store_dwordx4 v[150:151], v[226:229], off offset:32
	v_pk_mul_f32 v[96:97], v[96:97], v[148:149] op_sel_hi:[1,0]
	v_pk_mul_f32 v[98:99], v[98:99], v[148:149] op_sel_hi:[1,0]
	v_pk_mul_f32 v[100:101], v[100:101], v[148:149] op_sel_hi:[1,0]
	v_pk_mul_f32 v[102:103], v[102:103], v[148:149] op_sel_hi:[1,0]
	v_cvt_pk_bf16_f32 v230, v96, v97
	v_cvt_pk_bf16_f32 v231, v98, v99
	v_cvt_pk_bf16_f32 v232, v100, v101
	v_cvt_pk_bf16_f32 v233, v102, v103
	s_nop 1
	v_permlane32_swap_b32_e32 v230, v232
	v_permlane32_swap_b32_e32 v231, v233
	global_store_dwordx4 v[150:151], v[230:233], off offset:64
	v_pk_mul_f32 v[104:105], v[104:105], v[148:149] op_sel_hi:[1,0]
	v_pk_mul_f32 v[106:107], v[106:107], v[148:149] op_sel_hi:[1,0]
	v_pk_mul_f32 v[108:109], v[108:109], v[148:149] op_sel_hi:[1,0]
	v_pk_mul_f32 v[110:111], v[110:111], v[148:149] op_sel_hi:[1,0]
	v_cvt_pk_bf16_f32 v234, v104, v105
	v_cvt_pk_bf16_f32 v235, v106, v107
	v_cvt_pk_bf16_f32 v236, v108, v109
	v_cvt_pk_bf16_f32 v237, v110, v111
	s_nop 1
	v_permlane32_swap_b32_e32 v234, v236
	v_permlane32_swap_b32_e32 v235, v237
	global_store_dwordx4 v[150:151], v[234:237], off offset:96

; __device__ __forceinline__ void h_main(f32x16 (&acc0)[2][2], f32x16 (&acc1)[2][2], const WideCtx& c, int nk, char* lds) {
;   const int h = c.h;
;   for (int kt = 0; kt < nk; ++kt) {
;     asm volatile("s_waitcnt vmcnt(0)" ::: "memory");
;     __builtin_amdgcn_s_barrier();
;     if (kt + 1 < nk) h_stage(c, kt + 1);
;     const char* st = lds + (kt & 1) * 24576;
; #pragma unroll
;     for (int ks = 0; ks < 2; ++ks) {
;       bf16x8 wf[2], a0[2], a1[2];
; #pragma unroll
;       for (int b = 0; b < 2; ++b) {
;         wf[b] = *(const bf16x8*)(st + c.wro[b] + (((ks * 2 + h) ^ c.wsw[b]) << 4));
;         a0[b] = *(const bf16x8*)(st + c.aro[0][b] + (((ks * 2 + h) ^ c.asw[0][b]) << 4));
;         a1[b] = *(const bf16x8*)(st + c.aro[1][b] + (((ks * 2 + h) ^ c.asw[1][b]) << 4));
;       }
; #pragma unroll
;       for (int nb = 0; nb < 2; ++nb)
; #pragma unroll
;         for (int tb = 0; tb < 2; ++tb) {
;           acc0[nb][tb] = __builtin_amdgcn_mfma_f32_32x32x16_bf16(wf[nb], a0[tb], acc0[nb][tb], 0, 0, 0);
;           acc1[nb][tb] = __builtin_amdgcn_mfma_f32_32x32x16_bf16(wf[nb], a1[tb], acc1[nb][tb], 0, 0, 0);
;         }
;     }
;   }
; }
.LBB0_693:
	s_waitcnt vmcnt(6)
	s_barrier
	v_add_u32_e32 v171, s6, v248
	v_add_u32_e32 v196, s6, v249
	ds_read_b128 v[172:175], v171
	ds_read_b128 v[176:179], v196 offset:8192
	ds_read_b128 v[188:191], v196 offset:9216
	ds_read_b128 v[180:183], v196 offset:10240
	ds_read_b128 v[192:195], v196 offset:11264
	ds_read_b128 v[230:233], v196 offset:16384
	ds_read_b128 v[234:237], v196 offset:17408
	ds_read_b128 v[238:241], v196 offset:18432
	ds_read_b128 v[242:245], v196 offset:19456
	ds_read_b128 v[184:187], v171 offset:1024
	ds_read_b128 v[222:225], v171 offset:2048
	ds_read_b128 v[226:229], v171 offset:3072
	s_add_i32 s7, s6, 0xffffa000
	s_cmp_eq_u32 s6, 0
	s_cselect_b32 s7, 0xc000, s7
	s_add_i32 m0, s7, s33
	s_add_i32 s7, s6, 0x6000
	global_load_lds_dwordx4 v154, s[0:1]
	s_add_i32 m0, m0, 0x1000
	s_cmp_eq_u32 s6, 0xc000
	global_load_lds_dwordx4 v152, s[0:1]
	s_cselect_b32 s6, 0, s7
	s_add_i32 m0, m0, 0x1000
	s_waitcnt lgkmcnt(10)
	v_mfma_f32_16x16x32_bf16 v[112:115], v[172:175], v[176:179], v[112:115]
	global_load_lds_dwordx4 v150, s[0:1]
	s_add_i32 m0, m0, 0x1000
	s_waitcnt lgkmcnt(9)
	v_mfma_f32_16x16x32_bf16 v[116:119], v[172:175], v[188:191], v[116:119]
	global_load_lds_dwordx4 v148, s[0:1]
	s_add_i32 m0, m0, 0x1000
	s_waitcnt lgkmcnt(8)
	v_mfma_f32_16x16x32_bf16 v[80:83], v[172:175], v[180:183], v[80:83]
	global_load_lds_dwordx4 v146, s[0:1]
	s_add_i32 m0, m0, 0x1000
	s_waitcnt lgkmcnt(7)
	v_mfma_f32_16x16x32_bf16 v[84:87], v[172:175], v[192:195], v[84:87]
	global_load_lds_dwordx4 v144, s[0:1]
	s_add_u32 s0, s0, 64
	s_addc_u32 s1, s1, 0
	s_waitcnt lgkmcnt(6)
	v_mfma_f32_16x16x32_bf16 v[48:51], v[172:175], v[230:233], v[48:51]
	s_waitcnt lgkmcnt(5)
	v_mfma_f32_16x16x32_bf16 v[52:55], v[172:175], v[234:237], v[52:55]
	s_waitcnt lgkmcnt(4)
	v_mfma_f32_16x16x32_bf16 v[16:19], v[172:175], v[238:241], v[16:19]
	s_waitcnt lgkmcnt(3)
	v_mfma_f32_16x16x32_bf16 v[20:23], v[172:175], v[242:245], v[20:23]
	s_waitcnt lgkmcnt(2)
	v_mfma_f32_16x16x32_bf16 v[120:123], v[184:187], v[176:179], v[120:123]
	v_mfma_f32_16x16x32_bf16 v[124:127], v[184:187], v[188:191], v[124:127]
	v_mfma_f32_16x16x32_bf16 v[88:91], v[184:187], v[180:183], v[88:91]
	v_mfma_f32_16x16x32_bf16 v[92:95], v[184:187], v[192:195], v[92:95]
	v_mfma_f32_16x16x32_bf16 v[56:59], v[184:187], v[230:233], v[56:59]
	v_mfma_f32_16x16x32_bf16 v[60:63], v[184:187], v[234:237], v[60:63]
	v_mfma_f32_16x16x32_bf16 v[24:27], v[184:187], v[238:241], v[24:27]
	v_mfma_f32_16x16x32_bf16 v[28:31], v[184:187], v[242:245], v[28:31]
	s_waitcnt lgkmcnt(1)
	v_mfma_f32_16x16x32_bf16 v[96:99], v[222:225], v[176:179], v[96:99]
	v_mfma_f32_16x16x32_bf16 v[100:103], v[222:225], v[188:191], v[100:103]
	v_mfma_f32_16x16x32_bf16 v[64:67], v[222:225], v[180:183], v[64:67]
	v_mfma_f32_16x16x32_bf16 v[68:71], v[222:225], v[192:195], v[68:71]
	v_mfma_f32_16x16x32_bf16 v[32:35], v[222:225], v[230:233], v[32:35]
	v_mfma_f32_16x16x32_bf16 v[36:39], v[222:225], v[234:237], v[36:39]
	v_mfma_f32_16x16x32_bf16 v[0:3], v[222:225], v[238:241], v[0:3]
	v_mfma_f32_16x16x32_bf16 v[4:7], v[222:225], v[242:245], v[4:7]
	s_waitcnt lgkmcnt(0)
	v_mfma_f32_16x16x32_bf16 v[104:107], v[226:229], v[176:179], v[104:107]
	v_mfma_f32_16x16x32_bf16 v[108:111], v[226:229], v[188:191], v[108:111]
	v_mfma_f32_16x16x32_bf16 v[72:75], v[226:229], v[180:183], v[72:75]
	v_mfma_f32_16x16x32_bf16 v[76:79], v[226:229], v[192:195], v[76:79]
	v_mfma_f32_16x16x32_bf16 v[40:43], v[226:229], v[230:233], v[40:43]
	v_mfma_f32_16x16x32_bf16 v[44:47], v[226:229], v[234:237], v[44:47]
	v_mfma_f32_16x16x32_bf16 v[8:11], v[226:229], v[238:241], v[8:11]
	v_mfma_f32_16x16x32_bf16 v[12:15], v[226:229], v[242:245], v[12:15]
	s_add_i32 s9, s9, 1
	s_cmp_eq_u32 s9, 32
	s_cbranch_scc0 .LBB0_693
	s_waitcnt vmcnt(6)
	s_barrier
	v_add_u32_e32 v171, s6, v248
	v_add_u32_e32 v196, s6, v249
	ds_read_b128 v[172:175], v171
	ds_read_b128 v[176:179], v196 offset:8192
	ds_read_b128 v[188:191], v196 offset:9216
	ds_read_b128 v[180:183], v196 offset:10240
	ds_read_b128 v[192:195], v196 offset:11264
	ds_read_b128 v[230:233], v196 offset:16384
	ds_read_b128 v[234:237], v196 offset:17408
	ds_read_b128 v[238:241], v196 offset:18432
	ds_read_b128 v[242:245], v196 offset:19456
	ds_read_b128 v[184:187], v171 offset:1024
	ds_read_b128 v[222:225], v171 offset:2048
	ds_read_b128 v[226:229], v171 offset:3072
	s_add_i32 s7, s6, 0x6000
	s_cmp_eq_u32 s6, 0xc000
	s_cselect_b32 s6, 0, s7
	s_waitcnt lgkmcnt(10)
	v_mfma_f32_16x16x32_bf16 v[112:115], v[172:175], v[176:179], v[112:115]
	s_waitcnt lgkmcnt(9)
	v_mfma_f32_16x16x32_bf16 v[116:119], v[172:175], v[188:191], v[116:119]
	s_waitcnt lgkmcnt(8)
	v_mfma_f32_16x16x32_bf16 v[80:83], v[172:175], v[180:183], v[80:83]
	s_waitcnt lgkmcnt(7)
	v_mfma_f32_16x16x32_bf16 v[84:87], v[172:175], v[192:195], v[84:87]
	s_waitcnt lgkmcnt(6)
	v_mfma_f32_16x16x32_bf16 v[48:51], v[172:175], v[230:233], v[48:51]
	s_waitcnt lgkmcnt(5)
	v_mfma_f32_16x16x32_bf16 v[52:55], v[172:175], v[234:237], v[52:55]
	s_waitcnt lgkmcnt(4)
	v_mfma_f32_16x16x32_bf16 v[16:19], v[172:175], v[238:241], v[16:19]
	s_waitcnt lgkmcnt(3)
	v_mfma_f32_16x16x32_bf16 v[20:23], v[172:175], v[242:245], v[20:23]
	s_waitcnt lgkmcnt(2)
	v_mfma_f32_16x16x32_bf16 v[120:123], v[184:187], v[176:179], v[120:123]
	v_mfma_f32_16x16x32_bf16 v[124:127], v[184:187], v[188:191], v[124:127]
	v_mfma_f32_16x16x32_bf16 v[88:91], v[184:187], v[180:183], v[88:91]
	v_mfma_f32_16x16x32_bf16 v[92:95], v[184:187], v[192:195], v[92:95]
	v_mfma_f32_16x16x32_bf16 v[56:59], v[184:187], v[230:233], v[56:59]
	v_mfma_f32_16x16x32_bf16 v[60:63], v[184:187], v[234:237], v[60:63]
	v_mfma_f32_16x16x32_bf16 v[24:27], v[184:187], v[238:241], v[24:27]
	v_mfma_f32_16x16x32_bf16 v[28:31], v[184:187], v[242:245], v[28:31]
	s_waitcnt lgkmcnt(1)
	v_mfma_f32_16x16x32_bf16 v[96:99], v[222:225], v[176:179], v[96:99]
	v_mfma_f32_16x16x32_bf16 v[100:103], v[222:225], v[188:191], v[100:103]
	v_mfma_f32_16x16x32_bf16 v[64:67], v[222:225], v[180:183], v[64:67]
	v_mfma_f32_16x16x32_bf16 v[68:71], v[222:225], v[192:195], v[68:71]
	v_mfma_f32_16x16x32_bf16 v[32:35], v[222:225], v[230:233], v[32:35]
	v_mfma_f32_16x16x32_bf16 v[36:39], v[222:225], v[234:237], v[36:39]
	v_mfma_f32_16x16x32_bf16 v[0:3], v[222:225], v[238:241], v[0:3]
	v_mfma_f32_16x16x32_bf16 v[4:7], v[222:225], v[242:245], v[4:7]
	s_waitcnt lgkmcnt(0)
	v_mfma_f32_16x16x32_bf16 v[104:107], v[226:229], v[176:179], v[104:107]
	v_mfma_f32_16x16x32_bf16 v[108:111], v[226:229], v[188:191], v[108:111]
	v_mfma_f32_16x16x32_bf16 v[72:75], v[226:229], v[180:183], v[72:75]
	v_mfma_f32_16x16x32_bf16 v[76:79], v[226:229], v[192:195], v[76:79]
	v_mfma_f32_16x16x32_bf16 v[40:43], v[226:229], v[230:233], v[40:43]
	v_mfma_f32_16x16x32_bf16 v[44:47], v[226:229], v[234:237], v[44:47]
	v_mfma_f32_16x16x32_bf16 v[8:11], v[226:229], v[238:241], v[8:11]
	v_mfma_f32_16x16x32_bf16 v[12:15], v[226:229], v[242:245], v[12:15]
	s_waitcnt vmcnt(0)
	s_barrier
; __device__ __forceinline__ void h_main(f32x16 (&acc0)[2][2], f32x16 (&acc1)[2][2], const WideCtx& c, int nk, char* lds) {
;   const int h = c.h;
;   for (int kt = 0; kt < nk; ++kt) {
;     asm volatile("s_waitcnt vmcnt(0)" ::: "memory");
;     __builtin_amdgcn_s_barrier();
;     if (kt + 1 < nk) h_stage(c, kt + 1);
;     const char* st = lds + (kt & 1) * 24576;
; #pragma unroll
;     for (int ks = 0; ks < 2; ++ks) {
;       bf16x8 wf[2], a0[2], a1[2];
; #pragma unroll
;       for (int b = 0; b < 2; ++b) {
;         wf[b] = *(const bf16x8*)(st + c.wro[b] + (((ks * 2 + h) ^ c.wsw[b]) << 4));
;         a0[b] = *(const bf16x8*)(st + c.aro[0][b] + (((ks * 2 + h) ^ c.asw[0][b]) << 4));
;         a1[b] = *(const bf16x8*)(st + c.aro[1][b] + (((ks * 2 + h) ^ c.asw[1][b]) << 4));
;       }
; #pragma unroll
;       for (int nb = 0; nb < 2; ++nb)
; #pragma unroll
;         for (int tb = 0; tb < 2; ++tb) {
;           acc0[nb][tb] = __builtin_amdgcn_mfma_f32_32x32x16_bf16(wf[nb], a0[tb], acc0[nb][tb], 0, 0, 0);
;           acc1[nb][tb] = __builtin_amdgcn_mfma_f32_32x32x16_bf16(wf[nb], a1[tb], acc1[nb][tb], 0, 0, 0);
;         }
;     }
;   }
; }
	v_add_u32_e32 v171, s6, v248
	v_add_u32_e32 v196, s6, v249
	ds_read_b128 v[172:175], v171
	ds_read_b128 v[176:179], v196 offset:8192
	ds_read_b128 v[188:191], v196 offset:9216
	ds_read_b128 v[180:183], v196 offset:10240
	ds_read_b128 v[192:195], v196 offset:11264
	ds_read_b128 v[230:233], v196 offset:16384
	ds_read_b128 v[234:237], v196 offset:17408
	ds_read_b128 v[238:241], v196 offset:18432
	ds_read_b128 v[242:245], v196 offset:19456
	ds_read_b128 v[184:187], v171 offset:1024
	ds_read_b128 v[222:225], v171 offset:2048
	ds_read_b128 v[226:229], v171 offset:3072
	s_add_i32 s7, s6, 0x6000
	s_cmp_eq_u32 s6, 0xc000
	s_cselect_b32 s6, 0, s7
	s_waitcnt lgkmcnt(10)
	v_mfma_f32_16x16x32_bf16 v[112:115], v[172:175], v[176:179], v[112:115]
	s_waitcnt lgkmcnt(9)
	v_mfma_f32_16x16x32_bf16 v[116:119], v[172:175], v[188:191], v[116:119]
	s_waitcnt lgkmcnt(8)
	v_mfma_f32_16x16x32_bf16 v[80:83], v[172:175], v[180:183], v[80:83]
	s_waitcnt lgkmcnt(7)
	v_mfma_f32_16x16x32_bf16 v[84:87], v[172:175], v[192:195], v[84:87]
	s_waitcnt lgkmcnt(6)
	v_mfma_f32_16x16x32_bf16 v[48:51], v[172:175], v[230:233], v[48:51]
	s_waitcnt lgkmcnt(5)
	v_mfma_f32_16x16x32_bf16 v[52:55], v[172:175], v[234:237], v[52:55]
	s_waitcnt lgkmcnt(4)
	v_mfma_f32_16x16x32_bf16 v[16:19], v[172:175], v[238:241], v[16:19]
	s_waitcnt lgkmcnt(3)
	v_mfma_f32_16x16x32_bf16 v[20:23], v[172:175], v[242:245], v[20:23]
	s_waitcnt lgkmcnt(2)
	v_mfma_f32_16x16x32_bf16 v[120:123], v[184:187], v[176:179], v[120:123]
	v_mfma_f32_16x16x32_bf16 v[124:127], v[184:187], v[188:191], v[124:127]
	v_mfma_f32_16x16x32_bf16 v[88:91], v[184:187], v[180:183], v[88:91]
	v_mfma_f32_16x16x32_bf16 v[92:95], v[184:187], v[192:195], v[92:95]
	v_mfma_f32_16x16x32_bf16 v[56:59], v[184:187], v[230:233], v[56:59]
	v_mfma_f32_16x16x32_bf16 v[60:63], v[184:187], v[234:237], v[60:63]
	v_mfma_f32_16x16x32_bf16 v[24:27], v[184:187], v[238:241], v[24:27]
	v_mfma_f32_16x16x32_bf16 v[28:31], v[184:187], v[242:245], v[28:31]
	s_waitcnt lgkmcnt(1)
	v_mfma_f32_16x16x32_bf16 v[96:99], v[222:225], v[176:179], v[96:99]
	v_mfma_f32_16x16x32_bf16 v[100:103], v[222:225], v[188:191], v[100:103]
	v_mfma_f32_16x16x32_bf16 v[64:67], v[222:225], v[180:183], v[64:67]
	v_mfma_f32_16x16x32_bf16 v[68:71], v[222:225], v[192:195], v[68:71]
	v_mfma_f32_16x16x32_bf16 v[32:35], v[222:225], v[230:233], v[32:35]
	v_mfma_f32_16x16x32_bf16 v[36:39], v[222:225], v[234:237], v[36:39]
	v_mfma_f32_16x16x32_bf16 v[0:3], v[222:225], v[238:241], v[0:3]
	v_mfma_f32_16x16x32_bf16 v[4:7], v[222:225], v[242:245], v[4:7]
	s_waitcnt lgkmcnt(0)
; __device__ __forceinline__ void h_main(f32x16 (&acc0)[2][2], f32x16 (&acc1)[2][2], const WideCtx& c, int nk, char* lds) {
;     ...
;           acc0[nb][tb] = __builtin_amdgcn_mfma_f32_32x32x16_bf16(wf[nb], a0[tb], acc0[nb][tb], 0, 0, 0);
;           acc1[nb][tb] = __builtin_amdgcn_mfma_f32_32x32x16_bf16(wf[nb], a1[tb], acc1[nb][tb], 0, 0, 0);
; template <class F>
; __device__ __forceinline__ void gemm_phase_w(const u16* A, int lda, int M, const u16* W, int K, int N, char* lds, int* ctr, F&& epi) {
;     ...
;     const int ctm = tm, ctn = tn;
;     par ^= 1;
;     if (c.tid == 0) bw[2 + par] = atomicAdd(myctr, 1);
	v_mfma_f32_16x16x32_bf16 v[104:107], v[226:229], v[176:179], v[104:107]
	v_mfma_f32_16x16x32_bf16 v[108:111], v[226:229], v[188:191], v[108:111]
	v_mfma_f32_16x16x32_bf16 v[72:75], v[226:229], v[180:183], v[72:75]
	v_mfma_f32_16x16x32_bf16 v[76:79], v[226:229], v[192:195], v[76:79]
	v_mfma_f32_16x16x32_bf16 v[40:43], v[226:229], v[230:233], v[40:43]
	v_mfma_f32_16x16x32_bf16 v[44:47], v[226:229], v[234:237], v[44:47]
	v_mfma_f32_16x16x32_bf16 v[8:11], v[226:229], v[238:241], v[8:11]
	v_mfma_f32_16x16x32_bf16 v[12:15], v[226:229], v[242:245], v[12:15]
	s_xor_b32 s48, s48, 1
	s_nop 7
	s_nop 7
	v_permlane16_swap_b32_e32 v112, v116
	v_permlane16_swap_b32_e32 v113, v117
	v_permlane16_swap_b32_e32 v114, v118
	v_permlane16_swap_b32_e32 v115, v119
	v_permlane16_swap_b32_e32 v120, v124
	v_permlane16_swap_b32_e32 v121, v125
	v_permlane16_swap_b32_e32 v122, v126
	v_permlane16_swap_b32_e32 v123, v127
	v_permlane16_swap_b32_e32 v80, v84
	v_permlane16_swap_b32_e32 v81, v85
	v_permlane16_swap_b32_e32 v82, v86
	v_permlane16_swap_b32_e32 v83, v87
	v_permlane16_swap_b32_e32 v88, v92
	v_permlane16_swap_b32_e32 v89, v93
	v_permlane16_swap_b32_e32 v90, v94
	v_permlane16_swap_b32_e32 v91, v95
	v_permlane16_swap_b32_e32 v48, v52
	v_permlane16_swap_b32_e32 v49, v53
	v_permlane16_swap_b32_e32 v50, v54
	v_permlane16_swap_b32_e32 v51, v55
	v_permlane16_swap_b32_e32 v56, v60
	v_permlane16_swap_b32_e32 v57, v61
	v_permlane16_swap_b32_e32 v58, v62
	v_permlane16_swap_b32_e32 v59, v63
	v_permlane16_swap_b32_e32 v16, v20
	v_permlane16_swap_b32_e32 v17, v21
	v_permlane16_swap_b32_e32 v18, v22
	v_permlane16_swap_b32_e32 v19, v23
	v_permlane16_swap_b32_e32 v24, v28
	v_permlane16_swap_b32_e32 v25, v29
	v_permlane16_swap_b32_e32 v26, v30
	v_permlane16_swap_b32_e32 v27, v31
	v_permlane16_swap_b32_e32 v96, v100
	v_permlane16_swap_b32_e32 v97, v101
	v_permlane16_swap_b32_e32 v98, v102
	v_permlane16_swap_b32_e32 v99, v103
	v_permlane16_swap_b32_e32 v104, v108
	v_permlane16_swap_b32_e32 v105, v109
	v_permlane16_swap_b32_e32 v106, v110
	v_permlane16_swap_b32_e32 v107, v111
	v_permlane16_swap_b32_e32 v64, v68
	v_permlane16_swap_b32_e32 v65, v69
	v_permlane16_swap_b32_e32 v66, v70
	v_permlane16_swap_b32_e32 v67, v71
	v_permlane16_swap_b32_e32 v72, v76
	v_permlane16_swap_b32_e32 v73, v77
	v_permlane16_swap_b32_e32 v74, v78
	v_permlane16_swap_b32_e32 v75, v79
	v_permlane16_swap_b32_e32 v32, v36
	v_permlane16_swap_b32_e32 v33, v37
	v_permlane16_swap_b32_e32 v34, v38
	v_permlane16_swap_b32_e32 v35, v39
	v_permlane16_swap_b32_e32 v40, v44
	v_permlane16_swap_b32_e32 v41, v45
	v_permlane16_swap_b32_e32 v42, v46
	v_permlane16_swap_b32_e32 v43, v47
	v_permlane16_swap_b32_e32 v0, v4
	v_permlane16_swap_b32_e32 v1, v5
	v_permlane16_swap_b32_e32 v2, v6
	v_permlane16_swap_b32_e32 v3, v7
	v_permlane16_swap_b32_e32 v8, v12
	v_permlane16_swap_b32_e32 v9, v13
	v_permlane16_swap_b32_e32 v10, v14
	v_permlane16_swap_b32_e32 v11, v15
	v_permlane32_swap_b32_e32 v112, v116
	v_permlane32_swap_b32_e32 v113, v117
	v_permlane32_swap_b32_e32 v114, v118
	v_permlane32_swap_b32_e32 v115, v119
	v_permlane32_swap_b32_e32 v120, v124
	v_permlane32_swap_b32_e32 v121, v125
	v_permlane32_swap_b32_e32 v122, v126
	v_permlane32_swap_b32_e32 v123, v127
	v_permlane32_swap_b32_e32 v80, v84
	v_permlane32_swap_b32_e32 v81, v85
	v_permlane32_swap_b32_e32 v82, v86
	v_permlane32_swap_b32_e32 v83, v87
	v_permlane32_swap_b32_e32 v88, v92
	v_permlane32_swap_b32_e32 v89, v93
	v_permlane32_swap_b32_e32 v90, v94
	v_permlane32_swap_b32_e32 v91, v95
	v_permlane32_swap_b32_e32 v48, v52
	v_permlane32_swap_b32_e32 v49, v53
	v_permlane32_swap_b32_e32 v50, v54
	v_permlane32_swap_b32_e32 v51, v55
	v_permlane32_swap_b32_e32 v56, v60
	v_permlane32_swap_b32_e32 v57, v61
	v_permlane32_swap_b32_e32 v58, v62
	v_permlane32_swap_b32_e32 v59, v63
	v_permlane32_swap_b32_e32 v16, v20
	v_permlane32_swap_b32_e32 v17, v21
	v_permlane32_swap_b32_e32 v18, v22
	v_permlane32_swap_b32_e32 v19, v23
	v_permlane32_swap_b32_e32 v24, v28
	v_permlane32_swap_b32_e32 v25, v29
	v_permlane32_swap_b32_e32 v26, v30
	v_permlane32_swap_b32_e32 v27, v31
	v_permlane32_swap_b32_e32 v96, v100
	v_permlane32_swap_b32_e32 v97, v101
	v_permlane32_swap_b32_e32 v98, v102
	v_permlane32_swap_b32_e32 v99, v103
	v_permlane32_swap_b32_e32 v104, v108
	v_permlane32_swap_b32_e32 v105, v109
	v_permlane32_swap_b32_e32 v106, v110
	v_permlane32_swap_b32_e32 v107, v111
	v_permlane32_swap_b32_e32 v64, v68
	v_permlane32_swap_b32_e32 v65, v69
	v_permlane32_swap_b32_e32 v66, v70
	v_permlane32_swap_b32_e32 v67, v71
	v_permlane32_swap_b32_e32 v72, v76
	v_permlane32_swap_b32_e32 v73, v77
	v_permlane32_swap_b32_e32 v74, v78
	v_permlane32_swap_b32_e32 v75, v79
	v_permlane32_swap_b32_e32 v32, v36
	v_permlane32_swap_b32_e32 v33, v37
	v_permlane32_swap_b32_e32 v34, v38
	v_permlane32_swap_b32_e32 v35, v39
	v_permlane32_swap_b32_e32 v40, v44
	v_permlane32_swap_b32_e32 v41, v45
	v_permlane32_swap_b32_e32 v42, v46
	v_permlane32_swap_b32_e32 v43, v47
	v_permlane32_swap_b32_e32 v0, v4
	v_permlane32_swap_b32_e32 v1, v5
	v_permlane32_swap_b32_e32 v2, v6
	v_permlane32_swap_b32_e32 v3, v7
	v_permlane32_swap_b32_e32 v8, v12
	v_permlane32_swap_b32_e32 v9, v13
	v_permlane32_swap_b32_e32 v10, v14
	v_permlane32_swap_b32_e32 v11, v15
	v_lshl_add_u32 v247, v160, 8, v169
	v_and_or_b32 v246, v204, 31, v247
	v_ashrrev_i32_e32 v247, 31, v246
	v_lshl_add_u64 v[246:247], v[246:247], 2, s[44:45]
	global_load_dword v242, v[246:247], off
	global_load_dword v243, v[246:247], off offset:128
	global_load_dword v244, v[246:247], off offset:512
	global_load_dword v245, v[246:247], off offset:640
	s_and_saveexec_b64 s[6:7], vcc
	s_cbranch_execz .LBB0_698
	s_mov_b64 s[34:35], exec
	v_mbcnt_lo_u32_b32 v144, s34, 0
	v_mbcnt_hi_u32_b32 v144, s35, v144
	v_cmp_eq_u32_e64 s[38:39], 0, v144
	s_and_saveexec_b64 s[0:1], s[38:39]
	s_cbranch_execz .LBB0_697
	s_bcnt1_i32_b64 s9, s[34:35]
	v_mov_b32_e32 v145, s9
	global_atomic_add v145, v161, v145, s[30:31] offset:256 sc0
